# V^T pack via v_perm_b32; weight-conversion loops: loads issued together, small loops spread over thread ranges
# speedup vs baseline: 1.0870x; 1.0204x over previous
.LBB0_17:
	s_mov_b64 s[4:5], s[12:13]
	s_mov_b64 s[6:7], s[14:15]
	s_mov_b64 s[10:11], s[18:19]
	v_writelane_b32 v252, s4, 2
	s_mov_b64 s[2:3], s[14:15]
	v_mov_b32_e32 v42, v250
	v_writelane_b32 v252, s5, 3
	v_writelane_b32 v252, s6, 4
	v_writelane_b32 v252, s7, 5
	v_writelane_b32 v252, s8, 6
	v_writelane_b32 v252, s9, 7
	v_writelane_b32 v252, s10, 8
	s_lshl_b32 s38, s18, 8
	v_writelane_b32 v252, s11, 9
	v_lshl_add_u32 v43, s64, 8, v42
	v_subrev_u32_e32 v58, 0x4000, v43
	v_add_u32_e32 v63, s38, v58
	v_cmp_gt_i32_e32 vcc, 0, v58
	s_nop 1
	v_cndmask_b32_e32 v58, v58, v63, vcc
	v_add_u32_e32 v63, s38, v58
	v_cmp_gt_i32_e32 vcc, 0, v58
	s_nop 1
	v_cndmask_b32_e32 v58, v58, v63, vcc
	v_subrev_u32_e32 v59, 0x6000, v43
	v_add_u32_e32 v63, s38, v59
	v_cmp_gt_i32_e32 vcc, 0, v59
	s_nop 1
	v_cndmask_b32_e32 v59, v59, v63, vcc
	v_add_u32_e32 v63, s38, v59
	v_cmp_gt_i32_e32 vcc, 0, v59
	s_nop 1
	v_cndmask_b32_e32 v59, v59, v63, vcc
	v_subrev_u32_e32 v60, 0x8000, v43
	v_add_u32_e32 v63, s38, v60
	v_cmp_gt_i32_e32 vcc, 0, v60
	s_nop 1
	v_cndmask_b32_e32 v60, v60, v63, vcc
	v_add_u32_e32 v63, s38, v60
	v_cmp_gt_i32_e32 vcc, 0, v60
	s_nop 1
	v_cndmask_b32_e32 v60, v60, v63, vcc
	v_subrev_u32_e32 v61, 0x10000, v43
	v_add_u32_e32 v63, s38, v61
	v_cmp_gt_i32_e32 vcc, 0, v61
	s_nop 1
	v_cndmask_b32_e32 v61, v61, v63, vcc
	v_add_u32_e32 v63, s38, v61
	v_cmp_gt_i32_e32 vcc, 0, v61
	s_nop 1
	v_cndmask_b32_e32 v61, v61, v63, vcc
	v_lshlrev_b32_e32 v62, 2, v61
	s_mov_b32 s4, 0x1e000
	s_waitcnt lgkmcnt(0)
	s_cmp_lg_u64 s[86:87], 0
	v_cmp_gt_i32_e32 vcc, s4, v43
	s_cselect_b64 s[4:5], -1, 0
	v_cndmask_b32_e64 v0, 0, 1, s[4:5]
	v_lshlrev_b32_e32 v44, 2, v43
	v_cmp_ne_u32_e64 s[74:75], 1, v0
	s_and_saveexec_b64 s[6:7], vcc
	s_cbranch_execz .LBB0_58
	v_lshlrev_b32_e32 v38, 2, v43
	s_lshl_b32 s16, s38, 2
	v_lshlrev_b32_e32 v39, 3, v43
	s_lshl_b32 s17, s38, 3
	s_mov_b64 s[8:9], 0
	s_mov_b32 s18, 0x88888889
	s_movk_i32 s19, 0x15f
	s_movk_i32 s20, 0x8ff
	s_movk_i32 s21, 0xdff
	s_movk_i32 s22, 0xe1f
	s_movk_i32 s23, 0xe2c
	v_mov_b32_e32 v33, 0
	s_movk_i32 s24, 0x38b0
	s_mov_b32 s25, 0x1dfff
	v_mov_b32_e32 v40, v43
	s_branch .LBB0_20

.LBB0_34:
	s_or_b64 exec, exec, s[4:5]
	v_cmp_lt_i32_e64 s[4:5], -1, v32
	v_lshlrev_b32_e32 v34, 3, v41
	v_lshl_add_u64 v[36:37], v[32:33], 2, s[82:83]
	v_mov_b32_e32 v4, 0
	v_mov_b32_e32 v0, 0
	v_mov_b32_e32 v1, 0
	v_mov_b32_e32 v2, 0
	v_mov_b32_e32 v3, 0
	s_and_saveexec_b64 s[10:11], s[4:5]
	s_cbranch_execz .LBB0_37
	v_mad_i64_i32 v[0:1], s[12:13], v34, s24, v[36:37]
	global_load_dwordx4 v[0:3], v[0:1], off
	s_and_b64 vcc, exec, s[74:75]
	s_cbranch_vccnz .LBB0_37
	v_ashrrev_i32_e32 v35, 31, v34
	v_lshl_add_u64 v[6:7], v[34:35], 2, s[86:87]
	global_load_dword v50, v[6:7], off
.LBB0_37:
	s_or_b64 exec, exec, s[10:11]
	v_mov_b32_e32 v5, 0
	v_mov_b32_e32 v6, 0
	v_mov_b32_e32 v7, 0
	s_and_saveexec_b64 s[10:11], s[4:5]
	s_cbranch_execz .LBB0_40
	v_or_b32_e32 v4, 1, v34
	v_mad_i64_i32 v[4:5], s[12:13], v4, s24, v[36:37]
	global_load_dwordx4 v[4:7], v[4:5], off
	s_and_b64 vcc, exec, s[74:75]
	s_cbranch_vccnz .LBB0_40
	v_ashrrev_i32_e32 v35, 31, v34
	v_lshl_add_u64 v[8:9], v[34:35], 2, s[86:87]
	global_load_dword v51, v[8:9], off offset:4
.LBB0_40:
	s_or_b64 exec, exec, s[10:11]
	v_mov_b32_e32 v8, 0
	v_mov_b32_e32 v12, 0
	v_mov_b32_e32 v13, 0
	v_mov_b32_e32 v14, 0
	v_mov_b32_e32 v15, 0
	s_and_saveexec_b64 s[10:11], s[4:5]
	s_cbranch_execz .LBB0_43
	v_or_b32_e32 v9, 2, v34
	v_mad_i64_i32 v[10:11], s[12:13], v9, s24, v[36:37]
	global_load_dwordx4 v[12:15], v[10:11], off
	s_and_b64 vcc, exec, s[74:75]
	s_cbranch_vccnz .LBB0_43
	v_ashrrev_i32_e32 v35, 31, v34
	v_lshl_add_u64 v[10:11], v[34:35], 2, s[86:87]
	global_load_dword v52, v[10:11], off offset:8
.LBB0_43:
	s_or_b64 exec, exec, s[10:11]
	v_mov_b32_e32 v9, 0
	v_mov_b32_e32 v10, 0
	v_mov_b32_e32 v11, 0
	s_and_saveexec_b64 s[10:11], s[4:5]
	s_cbranch_execz .LBB0_46
	v_or_b32_e32 v8, 3, v34
	v_mad_i64_i32 v[8:9], s[12:13], v8, s24, v[36:37]
	global_load_dwordx4 v[8:11], v[8:9], off
	s_and_b64 vcc, exec, s[74:75]
	s_cbranch_vccnz .LBB0_46
	v_ashrrev_i32_e32 v35, 31, v34
	v_lshl_add_u64 v[16:17], v[34:35], 2, s[86:87]
	global_load_dword v53, v[16:17], off offset:12
.LBB0_46:
	s_or_b64 exec, exec, s[10:11]
	v_mov_b32_e32 v16, 0
	v_mov_b32_e32 v20, 0
	v_mov_b32_e32 v21, 0
	v_mov_b32_e32 v22, 0
	v_mov_b32_e32 v23, 0
	s_and_saveexec_b64 s[10:11], s[4:5]
	s_cbranch_execz .LBB0_49
	v_or_b32_e32 v17, 4, v34
	v_mad_i64_i32 v[18:19], s[12:13], v17, s24, v[36:37]
	global_load_dwordx4 v[20:23], v[18:19], off
	s_and_b64 vcc, exec, s[74:75]
	s_cbranch_vccnz .LBB0_49
	v_ashrrev_i32_e32 v35, 31, v34
	v_lshl_add_u64 v[18:19], v[34:35], 2, s[86:87]
	global_load_dword v54, v[18:19], off offset:16
.LBB0_49:
	s_or_b64 exec, exec, s[10:11]
	v_mov_b32_e32 v17, 0
	v_mov_b32_e32 v18, 0
	v_mov_b32_e32 v19, 0
	s_and_saveexec_b64 s[10:11], s[4:5]
	s_cbranch_execz .LBB0_52
	v_or_b32_e32 v16, 5, v34
	v_mad_i64_i32 v[16:17], s[12:13], v16, s24, v[36:37]
	global_load_dwordx4 v[16:19], v[16:17], off
	s_and_b64 vcc, exec, s[74:75]
	s_cbranch_vccnz .LBB0_52
	v_ashrrev_i32_e32 v35, 31, v34
	v_lshl_add_u64 v[24:25], v[34:35], 2, s[86:87]
	global_load_dword v55, v[24:25], off offset:20
.LBB0_52:
	s_or_b64 exec, exec, s[10:11]
	v_mov_b32_e32 v24, 0
	v_mov_b32_e32 v28, 0
	v_mov_b32_e32 v29, 0
	v_mov_b32_e32 v30, 0
	v_mov_b32_e32 v31, 0
	s_and_saveexec_b64 s[10:11], s[4:5]
	s_cbranch_execz .LBB0_55
	v_or_b32_e32 v25, 6, v34
	v_mad_i64_i32 v[26:27], s[12:13], v25, s24, v[36:37]
	global_load_dwordx4 v[28:31], v[26:27], off
	s_and_b64 vcc, exec, s[74:75]
	s_cbranch_vccnz .LBB0_55
	v_ashrrev_i32_e32 v35, 31, v34
	v_lshl_add_u64 v[26:27], v[34:35], 2, s[86:87]
	global_load_dword v56, v[26:27], off offset:24
.LBB0_55:
	s_or_b64 exec, exec, s[10:11]
	v_mov_b32_e32 v25, 0
	v_mov_b32_e32 v26, 0
	v_mov_b32_e32 v27, 0
	s_and_saveexec_b64 s[10:11], s[4:5]
	s_cbranch_execz .LBB0_19
	v_or_b32_e32 v24, 7, v34
	v_mad_i64_i32 v[24:25], s[4:5], v24, s24, v[36:37]
	global_load_dwordx4 v[24:27], v[24:25], off
	s_and_b64 vcc, exec, s[74:75]
	s_cbranch_vccnz .LBB0_19
	v_ashrrev_i32_e32 v35, 31, v34
	v_lshl_add_u64 v[34:35], v[34:35], 2, s[86:87]
	global_load_dword v57, v[34:35], off offset:28
	s_waitcnt vmcnt(0)
	v_mul_f32_e32 v2, v2, v50
	v_mul_f32_e32 v3, v3, v50
	v_mul_f32_e32 v0, v0, v50
	v_mul_f32_e32 v1, v1, v50
	v_mul_f32_e32 v6, v6, v51
	v_mul_f32_e32 v7, v7, v51
	v_mul_f32_e32 v4, v4, v51
	v_mul_f32_e32 v5, v5, v51
	v_mul_f32_e32 v14, v14, v52
	v_mul_f32_e32 v15, v15, v52
	v_mul_f32_e32 v12, v12, v52
	v_mul_f32_e32 v13, v13, v52
	v_mul_f32_e32 v10, v10, v53
	v_mul_f32_e32 v11, v11, v53
	v_mul_f32_e32 v8, v8, v53
	v_mul_f32_e32 v9, v9, v53
	v_mul_f32_e32 v22, v22, v54
	v_mul_f32_e32 v23, v23, v54
	v_mul_f32_e32 v20, v20, v54
	v_mul_f32_e32 v21, v21, v54
	v_mul_f32_e32 v18, v18, v55
	v_mul_f32_e32 v19, v19, v55
	v_mul_f32_e32 v16, v16, v55
	v_mul_f32_e32 v17, v17, v55
	v_mul_f32_e32 v30, v30, v56
	v_mul_f32_e32 v31, v31, v56
	v_mul_f32_e32 v28, v28, v56
	v_mul_f32_e32 v29, v29, v56
	v_mul_f32_e32 v26, v26, v57
	v_mul_f32_e32 v27, v27, v57
	v_mul_f32_e32 v24, v24, v57
	v_mul_f32_e32 v25, v25, v57
	s_branch .LBB0_19
.LBB0_58:
	s_or_b64 exec, exec, s[6:7]
	s_load_dwordx16 s[4:19], s[0:1], 0x40
	s_movk_i32 s0, 0xc00
	s_cmp_lg_u64 s[90:91], 0
	v_cmp_gt_i32_e32 vcc, s0, v58
	s_cselect_b64 s[0:1], -1, 0
	s_waitcnt lgkmcnt(0)
	v_writelane_b32 v252, s4, 10
	v_cndmask_b32_e64 v0, 0, 1, s[0:1]
	s_nop 0
	v_writelane_b32 v252, s5, 11
	v_writelane_b32 v252, s6, 12
	v_writelane_b32 v252, s7, 13
	v_writelane_b32 v252, s8, 14
	v_writelane_b32 v252, s9, 15
	v_writelane_b32 v252, s10, 16
	v_writelane_b32 v252, s11, 17
	v_writelane_b32 v252, s12, 18
	v_writelane_b32 v252, s13, 19
	v_writelane_b32 v252, s14, 20
	v_writelane_b32 v252, s15, 21
	v_writelane_b32 v252, s16, 22
	v_writelane_b32 v252, s17, 23
	v_writelane_b32 v252, s18, 24
	v_writelane_b32 v252, s19, 25
	s_mov_b64 s[6:7], 0
	v_cmp_ne_u32_e64 s[4:5], 1, v0
	s_and_saveexec_b64 s[8:9], vcc
	s_cbranch_execz .LBB0_85
	s_add_u32 s10, s2, 0x1300000
	s_addc_u32 s11, s3, 0
	v_lshlrev_b32_e32 v32, 2, v58
	s_lshl_b32 s14, s38, 2
	s_mov_b32 s15, 0x2aaaaaab
	s_movk_i32 s16, 0xffa0
	s_movk_i32 s17, 0xfe80
	v_mov_b32_e32 v33, 0
	s_movk_i32 s18, 0x600
	s_movk_i32 s19, 0xbff
	v_mov_b32_e32 v34, v58
	s_branch .LBB0_61

.LBB0_61:
	v_mul_hi_i32 v0, v34, s15
	v_lshrrev_b32_e32 v1, 31, v0
	v_ashrrev_i32_e32 v0, 4, v0
	v_add_u32_e32 v2, v0, v1
	v_mad_u64_u32 v[36:37], s[0:1], v2, s17, v[32:33]
	v_mad_u64_u32 v[0:1], s[0:1], v2, s16, v[34:35]
	v_lshlrev_b32_e32 v38, 3, v2
	v_mov_b32_e32 v37, v33
	v_cmp_lt_i32_e64 s[0:1], -1, v0
	v_lshl_add_u64 v[40:41], v[36:37], 2, s[94:95]
	v_ashrrev_i32_e32 v39, 31, v38
	v_mov_b32_e32 v0, 0
	v_mov_b32_e32 v1, 0
	v_mov_b32_e32 v2, 0
	v_mov_b32_e32 v3, 0
	s_and_saveexec_b64 s[12:13], s[0:1]
	s_cbranch_execz .LBB0_64
	v_mad_i64_i32 v[0:1], s[20:21], v38, s18, v[40:41]
	global_load_dwordx4 v[0:3], v[0:1], off
	s_and_b64 vcc, exec, s[4:5]
	s_cbranch_vccnz .LBB0_64
	v_lshl_add_u64 v[4:5], v[38:39], 2, s[90:91]
	global_load_dword v50, v[4:5], off
.LBB0_64:
	s_or_b64 exec, exec, s[12:13]
	v_mov_b32_e32 v4, 0
	v_mov_b32_e32 v8, 0
	v_mov_b32_e32 v9, 0
	v_mov_b32_e32 v10, 0
	v_mov_b32_e32 v11, 0
	s_and_saveexec_b64 s[12:13], s[0:1]
	s_cbranch_execz .LBB0_67
	v_or_b32_e32 v5, 1, v38
	v_mad_i64_i32 v[6:7], s[20:21], v5, s18, v[40:41]
	global_load_dwordx4 v[8:11], v[6:7], off
	s_and_b64 vcc, exec, s[4:5]
	s_cbranch_vccnz .LBB0_67
	v_lshl_add_u64 v[6:7], v[38:39], 2, s[90:91]
	global_load_dword v51, v[6:7], off offset:4
.LBB0_67:
	s_or_b64 exec, exec, s[12:13]
	v_mov_b32_e32 v5, 0
	v_mov_b32_e32 v6, 0
	v_mov_b32_e32 v7, 0
	s_and_saveexec_b64 s[12:13], s[0:1]
	s_cbranch_execz .LBB0_70
	v_or_b32_e32 v4, 2, v38
	v_mad_i64_i32 v[4:5], s[20:21], v4, s18, v[40:41]
	global_load_dwordx4 v[4:7], v[4:5], off
	s_and_b64 vcc, exec, s[4:5]
	s_cbranch_vccnz .LBB0_70
	v_lshl_add_u64 v[12:13], v[38:39], 2, s[90:91]
	global_load_dword v52, v[12:13], off offset:8
.LBB0_70:
	s_or_b64 exec, exec, s[12:13]
	v_mov_b32_e32 v12, 0
	v_mov_b32_e32 v16, 0
	v_mov_b32_e32 v17, 0
	v_mov_b32_e32 v18, 0
	v_mov_b32_e32 v19, 0
	s_and_saveexec_b64 s[12:13], s[0:1]
	s_cbranch_execz .LBB0_73
	v_or_b32_e32 v13, 3, v38
	v_mad_i64_i32 v[14:15], s[20:21], v13, s18, v[40:41]
	global_load_dwordx4 v[16:19], v[14:15], off
	s_and_b64 vcc, exec, s[4:5]
	s_cbranch_vccnz .LBB0_73
	v_lshl_add_u64 v[14:15], v[38:39], 2, s[90:91]
	global_load_dword v53, v[14:15], off offset:12
.LBB0_73:
	s_or_b64 exec, exec, s[12:13]
	v_mov_b32_e32 v13, 0
	v_mov_b32_e32 v14, 0
	v_mov_b32_e32 v15, 0
	s_and_saveexec_b64 s[12:13], s[0:1]
	s_cbranch_execz .LBB0_76
	v_or_b32_e32 v12, 4, v38
	v_mad_i64_i32 v[12:13], s[20:21], v12, s18, v[40:41]
	global_load_dwordx4 v[12:15], v[12:13], off
	s_and_b64 vcc, exec, s[4:5]
	s_cbranch_vccnz .LBB0_76
	v_lshl_add_u64 v[20:21], v[38:39], 2, s[90:91]
	global_load_dword v54, v[20:21], off offset:16
.LBB0_76:
	s_or_b64 exec, exec, s[12:13]
	v_mov_b32_e32 v20, 0
	v_mov_b32_e32 v24, 0
	v_mov_b32_e32 v25, 0
	v_mov_b32_e32 v26, 0
	v_mov_b32_e32 v27, 0
	s_and_saveexec_b64 s[12:13], s[0:1]
	s_cbranch_execz .LBB0_79
	v_or_b32_e32 v21, 5, v38
	v_mad_i64_i32 v[22:23], s[20:21], v21, s18, v[40:41]
	global_load_dwordx4 v[24:27], v[22:23], off
	s_and_b64 vcc, exec, s[4:5]
	s_cbranch_vccnz .LBB0_79
	v_lshl_add_u64 v[22:23], v[38:39], 2, s[90:91]
	global_load_dword v55, v[22:23], off offset:20
.LBB0_79:
	s_or_b64 exec, exec, s[12:13]
	v_mov_b32_e32 v21, 0
	v_mov_b32_e32 v22, 0
	v_mov_b32_e32 v23, 0
	s_and_saveexec_b64 s[12:13], s[0:1]
	s_cbranch_execz .LBB0_82
	v_or_b32_e32 v20, 6, v38
	v_mad_i64_i32 v[20:21], s[20:21], v20, s18, v[40:41]
	global_load_dwordx4 v[20:23], v[20:21], off
	s_and_b64 vcc, exec, s[4:5]
	s_cbranch_vccnz .LBB0_82
	v_lshl_add_u64 v[28:29], v[38:39], 2, s[90:91]
	global_load_dword v56, v[28:29], off offset:24
.LBB0_82:
	s_or_b64 exec, exec, s[12:13]
	v_mov_b32_e32 v28, 0
	v_mov_b32_e32 v29, 0
	v_mov_b32_e32 v30, 0
	v_mov_b32_e32 v31, 0
	s_and_saveexec_b64 s[12:13], s[0:1]
	s_cbranch_execz .LBB0_60
	v_or_b32_e32 v28, 7, v38
	v_mad_i64_i32 v[28:29], s[0:1], v28, s18, v[40:41]
	global_load_dwordx4 v[28:31], v[28:29], off
	s_and_b64 vcc, exec, s[4:5]
	s_cbranch_vccnz .LBB0_60
	v_lshl_add_u64 v[40:41], v[38:39], 2, s[90:91]
	global_load_dword v57, v[40:41], off offset:28
	s_waitcnt vmcnt(0)
	v_mul_f32_e32 v2, v2, v50
	v_mul_f32_e32 v3, v3, v50
	v_mul_f32_e32 v0, v0, v50
	v_mul_f32_e32 v1, v1, v50
	v_mul_f32_e32 v10, v10, v51
	v_mul_f32_e32 v11, v11, v51
	v_mul_f32_e32 v8, v8, v51
	v_mul_f32_e32 v9, v9, v51
	v_mul_f32_e32 v6, v6, v52
	v_mul_f32_e32 v7, v7, v52
	v_mul_f32_e32 v4, v4, v52
	v_mul_f32_e32 v5, v5, v52
	v_mul_f32_e32 v18, v18, v53
	v_mul_f32_e32 v19, v19, v53
	v_mul_f32_e32 v16, v16, v53
	v_mul_f32_e32 v17, v17, v53
	v_mul_f32_e32 v14, v14, v54
	v_mul_f32_e32 v15, v15, v54
	v_mul_f32_e32 v12, v12, v54
	v_mul_f32_e32 v13, v13, v54
	v_mul_f32_e32 v26, v26, v55
	v_mul_f32_e32 v27, v27, v55
	v_mul_f32_e32 v24, v24, v55
	v_mul_f32_e32 v25, v25, v55
	v_mul_f32_e32 v22, v22, v56
	v_mul_f32_e32 v23, v23, v56
	v_mul_f32_e32 v20, v20, v56
	v_mul_f32_e32 v21, v21, v56
	v_mul_f32_e32 v30, v30, v57
	v_mul_f32_e32 v31, v31, v57
	v_mul_f32_e32 v28, v28, v57
	v_mul_f32_e32 v29, v29, v57
	s_branch .LBB0_60
.LBB0_85:
	s_or_b64 exec, exec, s[8:9]
	s_movk_i32 s0, 0x800
	s_cmp_lg_u64 s[92:93], 0
	v_cmp_gt_i32_e32 vcc, s0, v59
	s_cselect_b64 s[0:1], -1, 0
	v_cndmask_b32_e64 v0, 0, 1, s[0:1]
	s_mov_b64 s[8:9], 0
	v_cmp_ne_u32_e64 s[6:7], 1, v0
	s_and_saveexec_b64 s[10:11], vcc
	s_cbranch_execz .LBB0_112
	s_add_u32 s12, s2, 0x1360000
	s_addc_u32 s13, s3, 0
	v_lshlrev_b32_e32 v38, 2, v59
	s_lshl_b32 s16, s38, 2
	v_mov_b32_e32 v33, 0
	s_movk_i32 s17, 0x7ff
	v_mov_b32_e32 v39, v59
	s_branch .LBB0_88

.LBB0_88:
	v_ashrrev_i32_e32 v0, 31, v39
	v_lshrrev_b32_e32 v0, 25, v0
	v_add_u32_e32 v0, v39, v0
	v_ashrrev_i32_e32 v1, 7, v0
	v_and_b32_e32 v0, 0xffffff80, v0
	v_lshlrev_b32_e32 v2, 9, v1
	v_readlane_b32 s40, v252, 10
	v_sub_u32_e32 v0, v39, v0
	v_sub_u32_e32 v32, v38, v2
	v_lshlrev_b32_e32 v34, 3, v1
	v_readlane_b32 s41, v252, 11
	v_cmp_lt_i32_e64 s[0:1], -1, v0
	v_ashrrev_i32_e32 v35, 31, v34
	v_lshl_add_u64 v[36:37], v[32:33], 2, s[40:41]
	v_mov_b32_e32 v0, 0
	v_mov_b32_e32 v1, 0
	v_mov_b32_e32 v2, 0
	v_mov_b32_e32 v3, 0
	v_readlane_b32 s42, v252, 12
	v_readlane_b32 s43, v252, 13
	v_readlane_b32 s44, v252, 14
	v_readlane_b32 s45, v252, 15
	v_readlane_b32 s46, v252, 16
	v_readlane_b32 s47, v252, 17
	v_readlane_b32 s48, v252, 18
	v_readlane_b32 s49, v252, 19
	v_readlane_b32 s50, v252, 20
	v_readlane_b32 s51, v252, 21
	v_readlane_b32 s52, v252, 22
	v_readlane_b32 s53, v252, 23
	v_readlane_b32 s54, v252, 24
	v_readlane_b32 s55, v252, 25
	s_and_saveexec_b64 s[14:15], s[0:1]
	s_cbranch_execz .LBB0_91
	v_lshlrev_b64 v[0:1], 11, v[34:35]
	v_lshl_add_u64 v[0:1], v[36:37], 0, v[0:1]
	global_load_dwordx4 v[0:3], v[0:1], off
	s_and_b64 vcc, exec, s[6:7]
	s_cbranch_vccnz .LBB0_91
	v_lshl_add_u64 v[4:5], v[34:35], 2, s[92:93]
	global_load_dword v50, v[4:5], off
.LBB0_91:
	s_or_b64 exec, exec, s[14:15]
	v_mov_b32_e32 v4, 0
	v_mov_b32_e32 v8, 0
	v_mov_b32_e32 v9, 0
	v_mov_b32_e32 v10, 0
	v_mov_b32_e32 v11, 0
	s_and_saveexec_b64 s[14:15], s[0:1]
	s_cbranch_execz .LBB0_94
	v_or_b32_e32 v6, 1, v34
	v_ashrrev_i32_e32 v7, 31, v6
	v_lshlrev_b64 v[6:7], 11, v[6:7]
	v_lshl_add_u64 v[6:7], v[36:37], 0, v[6:7]
	global_load_dwordx4 v[8:11], v[6:7], off
	s_and_b64 vcc, exec, s[6:7]
	s_cbranch_vccnz .LBB0_94
	v_lshl_add_u64 v[6:7], v[34:35], 2, s[92:93]
	global_load_dword v51, v[6:7], off offset:4
.LBB0_94:
	s_or_b64 exec, exec, s[14:15]
	v_mov_b32_e32 v5, 0
	v_mov_b32_e32 v6, 0
	v_mov_b32_e32 v7, 0
	s_and_saveexec_b64 s[14:15], s[0:1]
	s_cbranch_execz .LBB0_97
	v_or_b32_e32 v4, 2, v34
	v_ashrrev_i32_e32 v5, 31, v4
	v_lshlrev_b64 v[4:5], 11, v[4:5]
	v_lshl_add_u64 v[4:5], v[36:37], 0, v[4:5]
	global_load_dwordx4 v[4:7], v[4:5], off
	s_and_b64 vcc, exec, s[6:7]
	s_cbranch_vccnz .LBB0_97
	v_lshl_add_u64 v[12:13], v[34:35], 2, s[92:93]
	global_load_dword v52, v[12:13], off offset:8
.LBB0_97:
	s_or_b64 exec, exec, s[14:15]
	v_mov_b32_e32 v12, 0
	v_mov_b32_e32 v16, 0
	v_mov_b32_e32 v17, 0
	v_mov_b32_e32 v18, 0
	v_mov_b32_e32 v19, 0
	s_and_saveexec_b64 s[14:15], s[0:1]
	s_cbranch_execz .LBB0_100
	v_or_b32_e32 v14, 3, v34
	v_ashrrev_i32_e32 v15, 31, v14
	v_lshlrev_b64 v[14:15], 11, v[14:15]
	v_lshl_add_u64 v[14:15], v[36:37], 0, v[14:15]
	global_load_dwordx4 v[16:19], v[14:15], off
	s_and_b64 vcc, exec, s[6:7]
	s_cbranch_vccnz .LBB0_100
	v_lshl_add_u64 v[14:15], v[34:35], 2, s[92:93]
	global_load_dword v53, v[14:15], off offset:12
.LBB0_100:
	s_or_b64 exec, exec, s[14:15]
	v_mov_b32_e32 v13, 0
	v_mov_b32_e32 v14, 0
	v_mov_b32_e32 v15, 0
	s_and_saveexec_b64 s[14:15], s[0:1]
	s_cbranch_execz .LBB0_103
	v_or_b32_e32 v12, 4, v34
	v_ashrrev_i32_e32 v13, 31, v12
	v_lshlrev_b64 v[12:13], 11, v[12:13]
	v_lshl_add_u64 v[12:13], v[36:37], 0, v[12:13]
	global_load_dwordx4 v[12:15], v[12:13], off
	s_and_b64 vcc, exec, s[6:7]
	s_cbranch_vccnz .LBB0_103
	v_lshl_add_u64 v[20:21], v[34:35], 2, s[92:93]
	global_load_dword v54, v[20:21], off offset:16
.LBB0_103:
	s_or_b64 exec, exec, s[14:15]
	v_mov_b32_e32 v20, 0
	v_mov_b32_e32 v24, 0
	v_mov_b32_e32 v25, 0
	v_mov_b32_e32 v26, 0
	v_mov_b32_e32 v27, 0
	s_and_saveexec_b64 s[14:15], s[0:1]
	s_cbranch_execz .LBB0_106
	v_or_b32_e32 v22, 5, v34
	v_ashrrev_i32_e32 v23, 31, v22
	v_lshlrev_b64 v[22:23], 11, v[22:23]
	v_lshl_add_u64 v[22:23], v[36:37], 0, v[22:23]
	global_load_dwordx4 v[24:27], v[22:23], off
	s_and_b64 vcc, exec, s[6:7]
	s_cbranch_vccnz .LBB0_106
	v_lshl_add_u64 v[22:23], v[34:35], 2, s[92:93]
	global_load_dword v55, v[22:23], off offset:20
.LBB0_106:
	s_or_b64 exec, exec, s[14:15]
	v_mov_b32_e32 v21, 0
	v_mov_b32_e32 v22, 0
	v_mov_b32_e32 v23, 0
	s_and_saveexec_b64 s[14:15], s[0:1]
	s_cbranch_execz .LBB0_109
	v_or_b32_e32 v20, 6, v34
	v_ashrrev_i32_e32 v21, 31, v20
	v_lshlrev_b64 v[20:21], 11, v[20:21]
	v_lshl_add_u64 v[20:21], v[36:37], 0, v[20:21]
	global_load_dwordx4 v[20:23], v[20:21], off
	s_and_b64 vcc, exec, s[6:7]
	s_cbranch_vccnz .LBB0_109
	v_lshl_add_u64 v[28:29], v[34:35], 2, s[92:93]
	global_load_dword v56, v[28:29], off offset:24
.LBB0_109:
	s_or_b64 exec, exec, s[14:15]
	v_mov_b32_e32 v28, 0
	v_mov_b32_e32 v29, 0
	v_mov_b32_e32 v30, 0
	v_mov_b32_e32 v31, 0
	s_and_saveexec_b64 s[14:15], s[0:1]
	s_cbranch_execz .LBB0_87
	v_or_b32_e32 v28, 7, v34
	v_ashrrev_i32_e32 v29, 31, v28
	v_lshlrev_b64 v[28:29], 11, v[28:29]
	v_lshl_add_u64 v[28:29], v[36:37], 0, v[28:29]
	global_load_dwordx4 v[28:31], v[28:29], off
	s_and_b64 vcc, exec, s[6:7]
	s_cbranch_vccnz .LBB0_87
	v_lshl_add_u64 v[36:37], v[34:35], 2, s[92:93]
	global_load_dword v57, v[36:37], off offset:28
	s_waitcnt vmcnt(0)
	v_mul_f32_e32 v2, v2, v50
	v_mul_f32_e32 v3, v3, v50
	v_mul_f32_e32 v0, v0, v50
	v_mul_f32_e32 v1, v1, v50
	v_mul_f32_e32 v10, v10, v51
	v_mul_f32_e32 v11, v11, v51
	v_mul_f32_e32 v8, v8, v51
	v_mul_f32_e32 v9, v9, v51
	v_mul_f32_e32 v6, v6, v52
	v_mul_f32_e32 v7, v7, v52
	v_mul_f32_e32 v4, v4, v52
	v_mul_f32_e32 v5, v5, v52
	v_mul_f32_e32 v18, v18, v53
	v_mul_f32_e32 v19, v19, v53
	v_mul_f32_e32 v16, v16, v53
	v_mul_f32_e32 v17, v17, v53
	v_mul_f32_e32 v14, v14, v54
	v_mul_f32_e32 v15, v15, v54
	v_mul_f32_e32 v12, v12, v54
	v_mul_f32_e32 v13, v13, v54
	v_mul_f32_e32 v26, v26, v55
	v_mul_f32_e32 v27, v27, v55
	v_mul_f32_e32 v24, v24, v55
	v_mul_f32_e32 v25, v25, v55
	v_mul_f32_e32 v22, v22, v56
	v_mul_f32_e32 v23, v23, v56
	v_mul_f32_e32 v20, v20, v56
	v_mul_f32_e32 v21, v21, v56
	v_mul_f32_e32 v30, v30, v57
	v_mul_f32_e32 v31, v31, v57
	v_mul_f32_e32 v28, v28, v57
	v_mul_f32_e32 v29, v29, v57
	s_branch .LBB0_87
.LBB0_112:
	s_or_b64 exec, exec, s[10:11]
	s_movk_i32 s0, 0x3fff
	v_cmp_lt_i32_e32 vcc, s0, v60
	s_and_saveexec_b64 s[0:1], vcc
	s_xor_b64 s[0:1], exec, s[0:1]
	s_andn2_saveexec_b64 s[0:1], s[0:1]
	s_cbranch_execz .LBB0_150
	s_add_u32 s8, s2, 0x13a0000
	v_lshlrev_b32_e32 v38, 2, v60
	v_lshlrev_b32_e32 v39, 4, v60
	s_addc_u32 s9, s3, 0
	s_lshl_b32 s14, s38, 2
	s_lshl_b32 s15, s38, 4
	s_mov_b64 s[10:11], 0
	v_mov_b32_e32 v33, 0
	s_movk_i32 s16, 0x3fff
	v_mov_b32_e32 v40, v39
	v_mov_b32_e32 v41, v38
	v_mov_b32_e32 v45, v60
	s_branch .LBB0_115

.LBB0_131:
	s_or_b64 exec, exec, s[10:11]
	s_add_u32 s8, s2, 0x14a0000
	s_addc_u32 s9, s3, 0
	s_mov_b64 s[10:11], 0
	v_mov_b32_e32 v33, 0
	s_movk_i32 s16, 0x3fff
	v_mov_b32_e32 v40, v60
	s_branch .LBB0_133

.LBB0_150:
	s_or_b64 exec, exec, s[0:1]
	s_movk_i32 s0, 0x200
	v_cmp_gt_i32_e32 vcc, s0, v61
	s_movk_i32 s0, 0x1ff
	v_cmp_lt_i32_e64 s[0:1], s0, v61
	s_and_saveexec_b64 s[8:9], s[0:1]
	s_xor_b64 s[0:1], exec, s[8:9]
	s_andn2_saveexec_b64 s[8:9], s[0:1]
	s_cbranch_execz .LBB0_190
	s_add_u32 s10, s2, 0x17a0000
	s_addc_u32 s11, s3, 0
	s_lshl_b32 s16, s38, 2
	s_mov_b64 s[12:13], 0
	v_mov_b32_e32 v33, 0
	s_movk_i32 s17, 0x1ff
	v_mov_b32_e32 v38, v62
	v_mov_b32_e32 v39, v61
	s_branch .LBB0_155

.LBB0_171:
	s_or_b64 exec, exec, s[12:13]
	s_add_u32 s10, s2, 0x17a8000
	s_addc_u32 s11, s3, 0
	s_mov_b64 s[12:13], 0
	v_mov_b32_e32 v33, 0
	s_movk_i32 s17, 0x1ff
	v_mov_b32_e32 v38, v61
	s_branch .LBB0_173
.LBB0_172:
	s_or_b64 exec, exec, s[14:15]
	v_ashrrev_i32_e32 v47, 31, v32
	v_mov_b32_e32 v46, v32
	v_lshl_add_u64 v[40:41], v[34:35], 1, s[10:11]
	v_lshlrev_b64 v[46:47], 9, v[46:47]
	s_waitcnt vmcnt(0)
	v_cvt_pk_bf16_f32 v34, v0, v8
	v_cvt_pk_bf16_f32 v35, v4, v16
	v_cvt_pk_bf16_f32 v36, v12, v24
	v_cvt_pk_bf16_f32 v37, v20, v28
	v_lshl_add_u64 v[46:47], v[40:41], 0, v[46:47]
	v_add_u32_e32 v0, 1, v32
	global_store_dwordx4 v[46:47], v[34:37], off
	v_add_u32_e32 v4, 3, v32
	v_add_u32_e32 v38, s38, v38
	v_cvt_pk_bf16_f32 v34, v1, v9
	v_ashrrev_i32_e32 v1, 31, v0
	v_lshlrev_b64 v[0:1], 9, v[0:1]
	v_cvt_pk_bf16_f32 v35, v5, v17
	v_cvt_pk_bf16_f32 v36, v13, v25
	v_cvt_pk_bf16_f32 v37, v21, v29
	v_lshl_add_u64 v[0:1], v[40:41], 0, v[0:1]
	global_store_dwordx4 v[0:1], v[34:37], off
	v_add_u32_e32 v0, 2, v32
	v_ashrrev_i32_e32 v1, 31, v0
	v_lshlrev_b64 v[0:1], 9, v[0:1]
	v_ashrrev_i32_e32 v5, 31, v4
	v_cvt_pk_bf16_f32 v34, v2, v10
	v_cvt_pk_bf16_f32 v35, v6, v18
	v_cvt_pk_bf16_f32 v36, v14, v26
	v_cvt_pk_bf16_f32 v37, v22, v30
	v_lshl_add_u64 v[0:1], v[40:41], 0, v[0:1]
	v_lshlrev_b64 v[4:5], 9, v[4:5]
	v_cmp_lt_i32_e64 s[0:1], s17, v38
	global_store_dwordx4 v[0:1], v[34:37], off
	v_cvt_pk_bf16_f32 v0, v3, v11
	v_cvt_pk_bf16_f32 v1, v7, v19
	v_cvt_pk_bf16_f32 v2, v15, v27
	v_cvt_pk_bf16_f32 v3, v23, v31
	v_lshl_add_u64 v[4:5], v[40:41], 0, v[4:5]
	s_or_b64 s[12:13], s[0:1], s[12:13]
	v_add_u32_e32 v62, s16, v62
	global_store_dwordx4 v[4:5], v[0:3], off
	s_andn2_b64 exec, exec, s[12:13]
	s_cbranch_execz .LBB0_189
.LBB0_173:
	v_ashrrev_i32_e32 v0, 31, v38
	v_lshrrev_b32_e32 v0, 28, v0
	v_add_u32_e32 v0, v38, v0
	v_ashrrev_i32_e32 v1, 4, v0
	v_and_b32_e32 v0, -16, v0
	v_lshlrev_b32_e32 v2, 6, v1
	v_readlane_b32 s40, v252, 10
	v_sub_u32_e32 v0, v38, v0
	v_sub_u32_e32 v32, v62, v2
	v_lshlrev_b32_e32 v34, 3, v1
	v_readlane_b32 s52, v252, 22
	v_readlane_b32 s53, v252, 23
	v_cmp_lt_i32_e64 s[0:1], -1, v0
	v_ashrrev_i32_e32 v35, 31, v34
	v_lshl_add_u64 v[36:37], v[32:33], 2, s[52:53]
	v_mov_b32_e32 v0, 0
	v_mov_b32_e32 v1, 0
	v_mov_b32_e32 v2, 0
	v_mov_b32_e32 v3, 0
	v_readlane_b32 s41, v252, 11
	v_readlane_b32 s42, v252, 12
	v_readlane_b32 s43, v252, 13
	v_readlane_b32 s44, v252, 14
	v_readlane_b32 s45, v252, 15
	v_readlane_b32 s46, v252, 16
	v_readlane_b32 s47, v252, 17
	v_readlane_b32 s48, v252, 18
	v_readlane_b32 s49, v252, 19
	v_readlane_b32 s50, v252, 20
	v_readlane_b32 s51, v252, 21
	v_readlane_b32 s54, v252, 24
	v_readlane_b32 s55, v252, 25
	s_and_saveexec_b64 s[14:15], s[0:1]
	s_cbranch_execz .LBB0_175
	v_lshlrev_b64 v[0:1], 8, v[34:35]
	v_lshl_add_u64 v[0:1], v[36:37], 0, v[0:1]
	global_load_dwordx4 v[0:3], v[0:1], off

.LBB0_398:
	v_readlane_b32 s12, v254, 50
	v_ashrrev_i32_e32 v0, 1, v198
	s_lshl_b32 s13, s12, 7
	v_and_b32_e32 v11, 0xffffffe0, v0
	v_and_b32_e32 v10, 31, v198
	v_add_u32_e32 v0, s13, v11
	s_lshl_b32 s1, s10, 9
	s_and_b32 s0, s10, 3
	v_or_b32_e32 v0, v0, v10
	s_and_b32 s1, s1, 0x7ffff800
	s_mov_b64 s[10:11], 0x3e38aa3b
	v_bfe_u32 v12, v198, 5, 1
	s_add_i32 s8, s1, 0xffffc000
	s_mov_b32 s9, s11
	v_ashrrev_i32_e32 v1, 31, v0
	s_waitcnt vmcnt(0)
	v_lshl_add_u64 v[142:143], v[0:1], 0, s[8:9]
	s_lshl_b32 s10, s0, 6
	v_lshlrev_b32_e32 v1, 3, v12
	v_mov_b32_e32 v63, 0
	v_readfirstlane_b32 s11, v0
	s_cmp_lt_i32 s12, 0
	v_lshlrev_b32_e32 v140, 1, v1
	v_mov_b32_e32 v62, v63
	v_mov_b32_e32 v61, v63
	v_mov_b32_e32 v60, v63
	v_mov_b32_e32 v59, v63
	v_mov_b32_e32 v58, v63
	v_mov_b32_e32 v57, v63
	v_mov_b32_e32 v56, v63
	v_mov_b32_e32 v55, v63
	v_mov_b32_e32 v54, v63
	v_mov_b32_e32 v53, v63
	v_mov_b32_e32 v52, v63
	v_mov_b32_e32 v51, v63
	v_mov_b32_e32 v50, v63
	v_mov_b32_e32 v49, v63
	v_mov_b32_e32 v48, v63
	v_mov_b32_e32 v47, v63
	v_mov_b32_e32 v46, v63
	v_mov_b32_e32 v45, v63
	v_mov_b32_e32 v44, v63
	v_mov_b32_e32 v43, v63
	v_mov_b32_e32 v42, v63
	v_mov_b32_e32 v41, v63
	v_mov_b32_e32 v40, v63
	v_mov_b32_e32 v39, v63
	v_mov_b32_e32 v38, v63
	v_mov_b32_e32 v37, v63
	v_mov_b32_e32 v36, v63
	v_mov_b32_e32 v35, v63
	v_mov_b32_e32 v34, v63
	v_mov_b32_e32 v33, v63
	v_mov_b32_e32 v32, v63
	v_mov_b32_e32 v163, v63
	s_cbranch_scc1 .LBB0_411
	v_readlane_b32 s14, v253, 61
	v_readlane_b32 s15, v253, 62
	s_movk_i32 s18, 0x300
	v_readlane_b32 s16, v253, 63
	v_mov_b64_e32 v[0:1], s[14:15]
	v_mad_u64_u32 v[0:1], s[14:15], v142, s18, v[0:1]
	s_mul_i32 s14, s0, 0xc0
	s_mov_b64 s[0:1], 0x3e38aa3b
	s_mov_b32 s15, s1
	s_lshl_b64 s[0:1], s[8:9], 9
	v_readlane_b32 s17, v254, 0
	s_add_u32 s0, s16, s0
	v_mad_i32_i24 v1, v143, s18, v1
	s_addc_u32 s1, s17, s1
	s_lshl_b32 s9, s10, 1
	v_lshl_add_u64 v[0:1], v[0:1], 0, s[14:15]
	v_mov_b32_e32 v141, v193
	s_add_u32 s0, s0, s9
	v_lshl_add_u64 v[0:1], v[0:1], 0, v[140:141]
	s_addc_u32 s1, s1, 0
	s_mul_hi_u32 s9, s8, 0x300
	s_mulk_i32 s8, 0x300
	v_readlane_b32 s16, v254, 1
	s_mov_b32 s15, 0x2aaaaaab
	global_load_dwordx4 v[96:99], v[0:1], off
	global_load_dwordx4 v[100:103], v[0:1], off offset:32
	global_load_dwordx4 v[104:107], v[0:1], off offset:64
	global_load_dwordx4 v[108:111], v[0:1], off offset:96
	global_load_dwordx4 v[112:115], v[0:1], off offset:128
	global_load_dwordx4 v[116:119], v[0:1], off offset:160
	v_readlane_b32 s17, v254, 2
	s_add_u32 s8, s16, s8
	v_mul_hi_i32 v0, v198, s15
	s_addc_u32 s9, s17, s9
	v_lshrrev_b32_e32 v1, 31, v0
	v_ashrrev_i32_e32 v0, 1, v0
	s_add_u32 s8, s8, s14
	v_readlane_b32 s12, v254, 50
	v_add_u32_e32 v141, v0, v1
	s_addc_u32 s9, s9, 0
	s_lshl_b32 s14, s12, 1
	s_or_b32 s12, s13, 64
	v_mul_lo_u32 v0, v141, 12
	v_sub_u32_e32 v13, v198, v0
	v_add_u32_e32 v0, s12, v141
	v_mov_b64_e32 v[8:9], s[8:9]
	v_mad_i64_i32 v[2:3], s[16:17], v0, s18, v[8:9]
	v_lshlrev_b32_e32 v0, 3, v13
	v_ashrrev_i32_e32 v1, 31, v0
	v_lshlrev_b64 v[0:1], 1, v[0:1]
	v_lshl_add_u64 v[2:3], v[2:3], 0, v[0:1]
	global_load_dwordx4 v[14:17], v[2:3], off
	v_add_u32_e32 v2, 0x100, v198
	v_mul_hi_i32 v3, v2, s15
	v_lshrrev_b32_e32 v4, 31, v3
	v_ashrrev_i32_e32 v3, 1, v3
	v_add_u32_e32 v152, v3, v4
	v_mul_lo_u32 v3, v152, 12
	v_sub_u32_e32 v36, v2, v3
	v_add_u32_e32 v2, s12, v152
	v_mad_i64_i32 v[4:5], s[16:17], v2, s18, v[8:9]
	v_lshlrev_b32_e32 v2, 3, v36
	v_ashrrev_i32_e32 v3, 31, v2
	v_lshlrev_b64 v[2:3], 1, v[2:3]
	v_lshl_add_u64 v[4:5], v[4:5], 0, v[2:3]
	global_load_dwordx4 v[18:21], v[4:5], off
	v_add_u32_e32 v4, 0x200, v198
	v_mul_hi_i32 v5, v4, s15
	v_lshrrev_b32_e32 v6, 31, v5
	v_ashrrev_i32_e32 v5, 1, v5
	v_add_u32_e32 v153, v5, v6
	v_mul_lo_u32 v5, v153, 12
	v_sub_u32_e32 v37, v4, v5
	v_add_u32_e32 v4, s12, v153
	v_mad_i64_i32 v[6:7], s[16:17], v4, s18, v[8:9]
	v_lshlrev_b32_e32 v4, 3, v37
	v_ashrrev_i32_e32 v5, 31, v4
	v_lshlrev_b64 v[4:5], 1, v[4:5]
	v_lshlrev_b32_e32 v154, 1, v10
	v_lshl_add_u64 v[6:7], v[6:7], 0, v[4:5]
	v_or_b32_e32 v192, s12, v154
	global_load_dwordx4 v[22:25], v[6:7], off
	v_lshlrev_b64 v[6:7], 9, v[192:193]
	v_lshl_add_u64 v[26:27], s[0:1], 0, v[6:7]
	v_ashrrev_i32_e32 v6, 2, v198
	v_and_b32_e32 v34, -8, v6
	v_ashrrev_i32_e32 v35, 31, v34
	v_or_b32_e32 v192, 1, v192
	v_lshlrev_b64 v[6:7], 1, v[34:35]
	v_lshlrev_b64 v[30:31], 9, v[192:193]
	v_lshl_add_u64 v[26:27], v[26:27], 0, v[6:7]
	v_lshl_add_u64 v[30:31], s[0:1], 0, v[30:31]
	global_load_dwordx4 v[26:29], v[26:27], off
	v_lshl_add_u64 v[30:31], v[30:31], 0, v[6:7]
	global_load_dwordx4 v[30:33], v[30:31], off
	s_movk_i32 s12, 0xd0
	v_mul_lo_u32 v156, v141, s12
	v_lshlrev_b32_e32 v157, 4, v13
	v_add_u32_e32 v13, v156, v157
	v_mul_lo_u32 v158, v152, s12
	v_lshlrev_b32_e32 v159, 4, v36
	s_waitcnt lgkmcnt(0)
	s_barrier
	v_mul_lo_u32 v160, v153, s12
	v_lshlrev_b32_e32 v161, 4, v37
	v_mul_lo_u32 v155, v34, 34
	v_lshlrev_b32_e32 v162, 2, v10
	s_mov_b32 s12, 0x7060302
	v_or_b32_e32 v192, s13, v154
	v_lshlrev_b32_e32 v165, 2, v12
	v_lshl_add_u64 v[146:147], s[8:9], 0, v[0:1]
	v_mov_b32_e32 v163, 0
	v_lshl_add_u64 v[144:145], s[0:1], 0, v[6:7]
	v_mul_u32_u24_e32 v164, 0xd0, v10
	v_mul_u32_u24_e32 v166, 0x88, v10
	v_lshl_add_u64 v[148:149], s[8:9], 0, v[2:3]
	v_lshl_add_u64 v[150:151], s[8:9], 0, v[4:5]
	s_add_i32 s8, s13, 0x7f
	s_mov_b32 s9, 0
	v_mov_b32_e32 v169, 0xf149f2ca
	v_mov_b32_e32 v167, s14
	v_mov_b32_e32 v34, v163
	v_mov_b32_e32 v35, v163
	v_mov_b32_e32 v36, v163
	v_mov_b32_e32 v37, v163
	v_mov_b32_e32 v38, v163
	v_mov_b32_e32 v39, v163
	v_mov_b32_e32 v40, v163
	s_waitcnt vmcnt(4)
	ds_write_b128 v13, v[14:17]
	v_add_u32_e32 v13, v158, v159
	v_mov_b32_e32 v41, v163
	v_mov_b32_e32 v42, v163
	v_mov_b32_e32 v43, v163
	v_mov_b32_e32 v44, v163
	v_mov_b32_e32 v45, v163
	v_mov_b32_e32 v46, v163
	v_mov_b32_e32 v47, v163
	v_mov_b32_e32 v48, 0
	v_mov_b32_e32 v49, v163
	v_mov_b32_e32 v50, v163
	v_mov_b32_e32 v51, v163
	v_mov_b32_e32 v52, v163
	v_mov_b32_e32 v53, v163
	s_waitcnt vmcnt(3)
	ds_write_b128 v13, v[18:21]
	v_add_u32_e32 v13, v160, v161
	v_mov_b32_e32 v54, v163
	v_mov_b32_e32 v55, v163
	v_mov_b32_e32 v56, v163
	v_mov_b32_e32 v57, v163
	v_mov_b32_e32 v58, v163
	v_mov_b32_e32 v59, v163
	v_mov_b32_e32 v60, v163
	v_mov_b32_e32 v61, v163
	v_mov_b32_e32 v62, v163
	v_mov_b32_e32 v63, v163
	s_waitcnt vmcnt(2)
	ds_write_b128 v13, v[22:25]
	v_lshl_add_u32 v13, v155, 2, v162
	v_add_u32_e32 v13, 0x3400, v13
	s_waitcnt vmcnt(1)
	v_and_b32_e32 v14, 0xffff, v26
	s_waitcnt vmcnt(0)
	v_lshl_or_b32 v14, v30, 16, v14
	v_perm_b32 v15, v30, v26, s12
	ds_write2_b32 v13, v14, v15 offset1:34
	v_and_b32_e32 v14, 0xffff, v27
	v_lshl_or_b32 v14, v31, 16, v14
	v_perm_b32 v15, v31, v27, s12
	ds_write2_b32 v13, v14, v15 offset0:68 offset1:102
	v_and_b32_e32 v14, 0xffff, v28
	v_lshl_or_b32 v14, v32, 16, v14
	v_perm_b32 v15, v32, v28, s12
	ds_write2_b32 v13, v14, v15 offset0:136 offset1:170
	v_and_b32_e32 v14, 0xffff, v29
	v_lshl_or_b32 v14, v33, 16, v14
	v_perm_b32 v15, v33, v29, s12
	ds_write2_b32 v13, v14, v15 offset0:204 offset1:238
	v_add_u32_e32 v13, s13, v141
	v_mad_i64_i32 v[14:15], s[16:17], v13, s18, v[8:9]
	v_lshl_add_u64 v[14:15], v[14:15], 0, v[0:1]
	v_add_u32_e32 v13, s13, v152
	global_load_dwordx4 v[120:123], v[14:15], off
	v_mad_i64_i32 v[14:15], s[16:17], v13, s18, v[8:9]
	v_add_u32_e32 v13, s13, v153
	v_mad_i64_i32 v[8:9], s[16:17], v13, s18, v[8:9]
	v_lshl_add_u64 v[14:15], v[14:15], 0, v[2:3]
	v_lshl_add_u64 v[8:9], v[8:9], 0, v[4:5]
	global_load_dwordx4 v[124:127], v[14:15], off
	global_load_dwordx4 v[128:131], v[8:9], off
	v_lshlrev_b64 v[8:9], 9, v[192:193]
	v_lshl_add_u64 v[8:9], s[0:1], 0, v[8:9]
	v_lshl_add_u64 v[8:9], v[8:9], 0, v[6:7]
	v_or_b32_e32 v192, 1, v192
	global_load_dwordx4 v[132:135], v[8:9], off
	v_lshlrev_b64 v[8:9], 9, v[192:193]
	v_lshl_add_u64 v[8:9], s[0:1], 0, v[8:9]
	v_lshl_add_u64 v[8:9], v[8:9], 0, v[6:7]
	global_load_dwordx4 v[136:139], v[8:9], off
	v_add_u32_e32 v0, v11, v10
	v_sub_u32_e32 v0, v0, v165
	s_add_i32 s12, s11, 31
	v_subrev_u32_e32 v168, 64, v0
	v_mov_b32_e32 v32, 0
	v_mov_b32_e32 v33, v163
	s_waitcnt lgkmcnt(0)
	s_barrier
	s_branch .LBB0_401

.LBB0_407:
	v_cmp_gt_i32_e32 vcc, 0, v167
	s_cbranch_vccnz .LBB0_410
	s_xor_b32 s9, s9, 1
	s_mul_i32 s0, s9, 0x9000
	v_add3_u32 v1, s0, v156, v157
	s_waitcnt vmcnt(0)
	ds_write_b128 v1, v[120:123]
	v_add3_u32 v1, s0, v158, v159
	v_lshlrev_b32_e32 v0, 2, v155
	ds_write_b128 v1, v[124:127]
	v_add3_u32 v1, s0, v160, v161
	ds_write_b128 v1, v[128:131]
	v_add3_u32 v0, s0, v0, v162
	s_mov_b32 s1, 0x5040100
	s_mov_b32 s0, 0x7060302
	v_perm_b32 v1, v136, v132, s1
	v_perm_b32 v2, v136, v132, s0
	v_add_u32_e32 v0, 0x3400, v0
	ds_write2_b32 v0, v1, v2 offset1:34
	v_perm_b32 v1, v137, v133, s1
	v_perm_b32 v2, v137, v133, s0
	ds_write2_b32 v0, v1, v2 offset0:68 offset1:102
	v_perm_b32 v1, v138, v134, s1
	v_perm_b32 v2, v138, v134, s0
	ds_write2_b32 v0, v1, v2 offset0:136 offset1:170
	v_subrev_co_u32_e32 v167, vcc, 1, v167
	v_perm_b32 v1, v139, v135, s1
	v_perm_b32 v2, v139, v135, s0
	s_and_b64 vcc, exec, vcc
	ds_write2_b32 v0, v1, v2 offset0:204 offset1:238
	s_cbranch_vccnz .LBB0_400
	v_add_u32_e32 v0, s8, v141
	v_add_u32_e32 v0, 0xffffff41, v0
	s_movk_i32 s13, 0x300
	v_add_u32_e32 v2, s8, v152
	v_mad_i64_i32 v[0:1], s[0:1], v0, s13, v[146:147]
	v_add_u32_e32 v2, 0xffffff41, v2
	v_mad_i64_i32 v[2:3], s[0:1], v2, s13, v[148:149]
	global_load_dwordx4 v[120:123], v[0:1], off
	global_load_dwordx4 v[124:127], v[2:3], off
	v_add_u32_e32 v0, s8, v153
	v_add_u32_e32 v4, s8, v154
	v_add_u32_e32 v0, 0xffffff41, v0
	v_add_u32_e32 v192, 0xffffff41, v4
	v_mad_i64_i32 v[0:1], s[0:1], v0, s13, v[150:151]
	v_lshlrev_b64 v[2:3], 9, v[192:193]
	v_add_u32_e32 v192, 0xffffff42, v4
	v_lshl_add_u64 v[2:3], v[144:145], 0, v[2:3]
	global_load_dwordx4 v[128:131], v[0:1], off
	global_load_dwordx4 v[132:135], v[2:3], off
	v_lshlrev_b64 v[0:1], 9, v[192:193]
	v_lshl_add_u64 v[0:1], v[144:145], 0, v[0:1]
	global_load_dwordx4 v[136:139], v[0:1], off
	s_branch .LBB0_400

.LBB0_439:
	s_ff1_i32_b64 s0, s[72:73]
	v_readlane_b32 s1, v0, s0
	s_or_b32 s8, s8, s1
	s_lshl_b64 s[0:1], 1, s0
	s_andn2_b64 s[72:73], s[72:73], s[0:1]
	s_cmp_lg_u64 s[72:73], 0
	s_cbranch_scc1 .LBB0_439
	v_mbcnt_lo_u32_b32 v0, exec_lo, 0
	v_mbcnt_hi_u32_b32 v0, exec_hi, v0
	v_cmp_eq_u32_e32 vcc, 0, v0
	s_and_saveexec_b64 s[0:1], vcc
	s_xor_b64 s[0:1], exec, s[0:1]
	v_mov_b32_e32 v0, s8
	v_mov_b32_e32 v1, 0x11480
	ds_or_b32 v1, v0
	s_or_b64 exec, exec, s[0:1]
	v_readlane_b32 s0, v254, 52
	s_ashr_i32 s10, s0, 1
	v_readlane_b32 s0, v254, 53
	v_mov_b32_e32 v0, 0x11480
	v_readlane_b32 s1, v254, 54
	s_mov_b32 s8, s0
	s_waitcnt lgkmcnt(0)
	s_barrier
	ds_read_b32 v0, v0
	s_mul_i32 s1, s8, 0xe80000
	v_readlane_b32 s8, v254, 3
	s_mul_hi_i32 s0, s0, 0xe80000
	v_readlane_b32 s9, v254, 4
	s_add_u32 s13, s8, s1
	s_addc_u32 s14, s9, s0
	s_lshl_b32 s0, 2, s10
	s_add_i32 s0, s0, -1
	s_cmp_lt_i32 s10, 31
	s_cselect_b32 s0, s0, -1
	s_waitcnt lgkmcnt(0)
	v_readfirstlane_b32 s1, v0
	s_and_b32 s12, s1, s0
	v_ashrrev_i32_e32 v0, 31, v151
	v_readfirstlane_b32 s11, v206
	s_cmp_eq_u32 s12, 0
	v_lshlrev_b32_e32 v238, 2, v150
	v_lshlrev_b32_e32 v239, 1, v150
	v_lshrrev_b32_e32 v152, 29, v0
	s_cbranch_scc1 .LBB0_457
	v_or_b32_e32 v0, 0x11400, v238
	s_add_u32 s0, s13, 0x1000
	ds_read_b32 v153, v0
	s_addc_u32 s1, s14, 0
	v_ashrrev_i32_e32 v0, 31, v198
	s_add_u32 s8, s13, 0x1080
	s_flbit_i32_b32 s15, s12
	v_lshrrev_b32_e32 v0, 29, v0
	s_addc_u32 s9, s14, 0
	s_xor_b32 s19, s15, 31
	v_add_u32_e32 v0, v198, v0
	s_lshl_b32 s15, s19, 6
	v_ashrrev_i32_e32 v154, 3, v0
	v_and_b32_e32 v0, -8, v0
	v_sub_u32_e32 v8, v198, v0
	v_add_u32_e32 v0, s15, v154
	v_mov_b64_e32 v[2:3], s[0:1]
	s_movk_i32 s22, 0x1d00
	v_mad_i64_i32 v[4:5], s[16:17], v0, s22, v[2:3]
	v_lshlrev_b32_e32 v0, 3, v8
	v_ashrrev_i32_e32 v1, 31, v0
	v_lshl_add_u64 v[4:5], v[0:1], 1, v[4:5]
	global_load_dwordx4 v[128:131], v[4:5], off
	v_add_u32_e32 v4, v151, v152
	v_ashrrev_i32_e32 v155, 3, v4
	v_and_b32_e32 v4, -8, v4
	v_sub_u32_e32 v9, v151, v4
	v_add_u32_e32 v4, s15, v155
	v_mad_i64_i32 v[4:5], s[16:17], v4, s22, v[2:3]
	v_lshlrev_b32_e32 v2, 3, v9
	v_ashrrev_i32_e32 v3, 31, v2
	v_lshl_add_u64 v[4:5], v[2:3], 1, v[4:5]
	global_load_dwordx4 v[132:135], v[4:5], off
	v_or_b32_e32 v4, s15, v239
	v_mul_u32_u24_e32 v192, 0x1d00, v4
	v_ashrrev_i32_e32 v4, 2, v198
	v_and_b32_e32 v4, -8, v4
	v_lshl_add_u64 v[6:7], s[8:9], 0, v[192:193]
	v_ashrrev_i32_e32 v5, 31, v4
	v_lshl_add_u64 v[6:7], v[4:5], 1, v[6:7]
	s_movk_i32 s15, 0x1000
	global_load_dwordx4 v[136:139], v[6:7], off
	v_add_co_u32_e32 v6, vcc, s15, v6
	s_movk_i32 s15, 0x90
	s_nop 0
	v_addc_co_u32_e32 v7, vcc, 0, v7, vcc
	global_load_dwordx4 v[140:143], v[6:7], off offset:3328
	v_mul_lo_u32 v157, v154, s15
	v_lshlrev_b32_e32 v158, 4, v8
	v_add_u32_e32 v6, v157, v158
	v_mul_lo_u32 v159, v155, s15
	v_lshlrev_b32_e32 v176, 4, v9
	s_waitcnt lgkmcnt(0)
	s_barrier
	v_mul_lo_u32 v156, v4, 34
	s_mov_b32 s15, 0x7060302
	s_waitcnt vmcnt(3)
	ds_write_b128 v6, v[128:131]
	v_add_u32_e32 v6, v159, v176
	s_waitcnt vmcnt(2)
	ds_write_b128 v6, v[132:135]
	v_lshl_add_u32 v6, v156, 2, v238
	v_add_u32_e32 v6, 0x3400, v6
	s_waitcnt vmcnt(1)
	v_and_b32_e32 v7, 0xffff, v136
	s_waitcnt vmcnt(0)
	v_lshl_or_b32 v7, v140, 16, v7
	v_perm_b32 v8, v140, v136, s15
	ds_write2_b32 v6, v7, v8 offset1:34
	v_and_b32_e32 v7, 0xffff, v137
	v_lshl_or_b32 v7, v141, 16, v7
	v_perm_b32 v8, v141, v137, s15
	ds_write2_b32 v6, v7, v8 offset0:68 offset1:102
	v_and_b32_e32 v7, 0xffff, v138
	v_lshl_or_b32 v7, v142, 16, v7
	v_perm_b32 v8, v142, v138, s15
	ds_write2_b32 v6, v7, v8 offset0:136 offset1:170
	v_perm_b32 v8, v143, v139, s15
	s_lshl_b32 s15, -1, s19
	s_andn2_b32 s15, s12, s15
	s_flbit_i32_b32 s16, s15
	s_xor_b32 s16, s16, 31
	s_cmp_lg_u32 s15, 0
	v_and_b32_e32 v7, 0xffff, v139
	s_cselect_b32 s18, s16, -1
	v_lshl_or_b32 v7, v143, 16, v7
	s_cmp_lt_i32 s18, 0
	ds_write2_b32 v6, v7, v8 offset0:204 offset1:238
	s_cbranch_scc1 .LBB0_445
	s_lshl_b32 s15, s18, 6
	v_add_u32_e32 v8, s15, v154
	v_mov_b64_e32 v[6:7], s[0:1]
	v_add_u32_e32 v10, s15, v155
	v_mad_i64_i32 v[8:9], s[16:17], v8, s22, v[6:7]
	v_mad_i64_i32 v[6:7], s[16:17], v10, s22, v[6:7]
	v_lshl_add_u64 v[8:9], v[0:1], 1, v[8:9]
	v_lshl_add_u64 v[6:7], v[2:3], 1, v[6:7]
	global_load_dwordx4 v[128:131], v[8:9], off
	global_load_dwordx4 v[132:135], v[6:7], off
	v_or_b32_e32 v12, s15, v239
	v_mov_b64_e32 v[6:7], s[8:9]
	v_mad_u64_u32 v[8:9], s[16:17], v12, s22, v[6:7]
	v_lshlrev_b64 v[10:11], 1, v[4:5]
	v_or_b32_e32 v12, 1, v12
	v_lshl_add_u64 v[8:9], v[8:9], 0, v[10:11]
	v_mad_u64_u32 v[6:7], s[16:17], v12, s22, v[6:7]
	v_lshl_add_u64 v[6:7], v[6:7], 0, v[10:11]
	global_load_dwordx4 v[136:139], v[8:9], off
	global_load_dwordx4 v[140:143], v[6:7], off

.LBB0_453:
	s_cmp_lt_i32 s17, 0
	s_cbranch_scc1 .LBB0_446
	s_xor_b32 s16, s16, 1
	s_mul_i32 s0, s16, 0x9000
	v_add3_u32 v1, s0, v157, v158
	v_lshlrev_b32_e32 v0, 2, v156
	s_waitcnt vmcnt(0)
	ds_write_b128 v1, v[128:131]
	v_add3_u32 v1, s0, v159, v176
	ds_write_b128 v1, v[132:135]
	v_add3_u32 v0, s0, v0, v238
	s_mov_b32 s1, 0x5040100
	s_mov_b32 s0, 0x7060302
	v_perm_b32 v1, v140, v136, s1
	v_perm_b32 v2, v140, v136, s0
	v_add_u32_e32 v0, 0x3400, v0
	ds_write2_b32 v0, v1, v2 offset1:34
	v_perm_b32 v1, v141, v137, s1
	v_perm_b32 v2, v141, v137, s0
	ds_write2_b32 v0, v1, v2 offset0:68 offset1:102
	v_perm_b32 v1, v142, v138, s1
	v_perm_b32 v2, v142, v138, s0
	ds_write2_b32 v0, v1, v2 offset0:136 offset1:170
	v_perm_b32 v2, v143, v139, s0
	s_lshl_b32 s0, -1, s17
	s_andn2_b32 s0, s12, s0
	v_perm_b32 v1, v143, v139, s1
	s_flbit_i32_b32 s1, s0
	s_xor_b32 s1, s1, 31
	s_cmp_lg_u32 s0, 0
	s_cselect_b32 s18, s1, -1
	s_cmp_lt_i32 s18, 0
	ds_write2_b32 v0, v1, v2 offset0:204 offset1:238
	s_cbranch_scc1 .LBB0_456
	s_lshl_b32 s8, s18, 6
	v_add_u32_e32 v0, s8, v154
	s_movk_i32 s9, 0x1d00
	v_add_u32_e32 v2, s8, v155
	v_mad_i64_i32 v[0:1], s[0:1], v0, s9, v[146:147]
	v_mad_i64_i32 v[2:3], s[0:1], v2, s9, v[148:149]
	global_load_dwordx4 v[128:131], v[0:1], off
	global_load_dwordx4 v[132:135], v[2:3], off
	v_or_b32_e32 v2, s8, v239
	v_mad_u64_u32 v[0:1], s[0:1], v2, s9, v[144:145]
	v_or_b32_e32 v2, 1, v2
	v_mad_u64_u32 v[2:3], s[0:1], v2, s9, v[144:145]
	global_load_dwordx4 v[136:139], v[0:1], off
	global_load_dwordx4 v[140:143], v[2:3], off

.LBB0_458:
	ds_bpermute_b32 v195, v236, v207
	v_readlane_b32 s0, v254, 55
	s_addk_i32 s0, 0xfe01
	s_ashr_i32 s0, s0, 6
	s_max_i32 s11, s0, 0
	v_mov_b32_e32 v127, 0
	v_readfirstlane_b32 s12, v206
	s_cmp_lt_i32 s10, s11
	v_mov_b32_e32 v126, v127
	v_mov_b32_e32 v125, v127
	v_mov_b32_e32 v124, v127
	v_mov_b32_e32 v123, v127
	v_mov_b32_e32 v122, v127
	v_mov_b32_e32 v121, v127
	v_mov_b32_e32 v120, v127
	v_mov_b32_e32 v119, v127
	v_mov_b32_e32 v118, v127
	v_mov_b32_e32 v117, v127
	v_mov_b32_e32 v116, v127
	v_mov_b32_e32 v115, v127
	v_mov_b32_e32 v114, v127
	v_mov_b32_e32 v113, v127
	v_mov_b32_e32 v112, v127
	v_mov_b32_e32 v79, v127
	v_mov_b32_e32 v78, v127
	v_mov_b32_e32 v77, v127
	v_mov_b32_e32 v76, v127
	v_mov_b32_e32 v75, v127
	v_mov_b32_e32 v74, v127
	v_mov_b32_e32 v73, v127
	v_mov_b32_e32 v72, v127
	v_mov_b32_e32 v71, v127
	v_mov_b32_e32 v70, v127
	v_mov_b32_e32 v69, v127
	v_mov_b32_e32 v68, v127
	v_mov_b32_e32 v67, v127
	v_mov_b32_e32 v66, v127
	v_mov_b32_e32 v65, v127
	v_mov_b32_e32 v64, v127
	v_mov_b32_e32 v209, v127
	s_cbranch_scc1 .LBB0_475
	s_add_u32 s0, s13, 0x1100
	v_ashrrev_i32_e32 v0, 31, v198
	s_addc_u32 s1, s14, 0
	v_lshrrev_b32_e32 v0, 29, v0
	s_add_u32 s8, s13, 0x1180
	v_add_u32_e32 v0, v198, v0
	s_addc_u32 s9, s14, 0
	s_lshl_b32 s13, s10, 6
	v_ashrrev_i32_e32 v192, 3, v0
	v_and_b32_e32 v0, -8, v0
	v_sub_u32_e32 v12, v198, v0
	v_add_u32_e32 v0, s13, v192
	v_mov_b64_e32 v[2:3], s[0:1]
	s_movk_i32 s18, 0x1d00
	v_mad_i64_i32 v[4:5], s[14:15], v0, s18, v[2:3]
	v_lshlrev_b32_e32 v0, 3, v12
	v_ashrrev_i32_e32 v1, 31, v0
	v_lshl_add_u64 v[4:5], v[0:1], 1, v[4:5]
	global_load_dwordx4 v[176:179], v[4:5], off
	v_add_u32_e32 v4, v151, v152
	v_ashrrev_i32_e32 v240, 3, v4
	v_and_b32_e32 v4, -8, v4
	v_sub_u32_e32 v13, v151, v4
	v_add_u32_e32 v4, s13, v240
	v_mad_i64_i32 v[4:5], s[14:15], v4, s18, v[2:3]
	v_lshlrev_b32_e32 v2, 3, v13
	v_ashrrev_i32_e32 v3, 31, v2
	v_lshl_add_u64 v[4:5], v[2:3], 1, v[4:5]
	global_load_dwordx4 v[180:183], v[4:5], off
	v_ashrrev_i32_e32 v4, 2, v198
	v_and_b32_e32 v4, -8, v4
	v_or_b32_e32 v14, s13, v239
	v_mov_b64_e32 v[8:9], s[8:9]
	v_ashrrev_i32_e32 v5, 31, v4
	v_mad_u64_u32 v[10:11], s[14:15], v14, s18, v[8:9]
	v_lshlrev_b64 v[6:7], 1, v[4:5]
	v_lshl_add_u64 v[10:11], v[10:11], 0, v[6:7]
	global_load_dwordx4 v[184:187], v[10:11], off
	v_or_b32_e32 v10, 1, v14
	v_mad_u64_u32 v[8:9], s[14:15], v10, s18, v[8:9]
	v_lshl_add_u64 v[8:9], v[8:9], 0, v[6:7]
	global_load_dwordx4 v[188:191], v[8:9], off
	s_movk_i32 s13, 0x90
	v_mul_lo_u32 v242, v192, s13
	v_lshlrev_b32_e32 v243, 4, v12
	v_add_u32_e32 v8, v242, v243
	v_mul_lo_u32 v244, v240, s13
	v_lshlrev_b32_e32 v245, 4, v13
	s_waitcnt lgkmcnt(0)
	s_barrier
	v_mul_lo_u32 v241, v4, 34
	s_mov_b32 s13, 0x7060302
	s_waitcnt vmcnt(3)
	ds_write_b128 v8, v[176:179]
	v_add_u32_e32 v8, v244, v245
	s_waitcnt vmcnt(2)
	ds_write_b128 v8, v[180:183]
	v_lshl_add_u32 v8, v241, 2, v238
	v_add_u32_e32 v8, 0x3400, v8
	s_waitcnt vmcnt(1)
	v_and_b32_e32 v9, 0xffff, v184
	s_waitcnt vmcnt(0)
	v_lshl_or_b32 v9, v188, 16, v9
	v_perm_b32 v10, v188, v184, s13
	ds_write2_b32 v8, v9, v10 offset1:34
	v_and_b32_e32 v9, 0xffff, v185
	v_lshl_or_b32 v9, v189, 16, v9
	v_perm_b32 v10, v189, v185, s13
	ds_write2_b32 v8, v9, v10 offset0:68 offset1:102
	v_and_b32_e32 v9, 0xffff, v186
	v_lshl_or_b32 v9, v190, 16, v9
	v_perm_b32 v10, v190, v186, s13
	ds_write2_b32 v8, v9, v10 offset0:136 offset1:170
	v_perm_b32 v10, v191, v187, s13
	s_add_i32 s13, s10, -1
	s_cmp_gt_u32 s10, s11
	v_and_b32_e32 v9, 0xffff, v187
	s_cselect_b32 s14, s13, -1
	v_lshl_or_b32 v9, v191, 16, v9
	s_cmp_lt_i32 s14, 0
	ds_write2_b32 v8, v9, v10 offset0:204 offset1:238
	s_cbranch_scc1 .LBB0_461
	s_lshl_b32 s13, s14, 6
	v_add_u32_e32 v10, s13, v192
	v_mov_b64_e32 v[8:9], s[0:1]
	v_add_u32_e32 v12, s13, v240
	v_mad_i64_i32 v[10:11], s[16:17], v10, s18, v[8:9]
	v_mad_i64_i32 v[8:9], s[16:17], v12, s18, v[8:9]
	v_lshl_add_u64 v[10:11], v[0:1], 1, v[10:11]
	v_lshl_add_u64 v[8:9], v[2:3], 1, v[8:9]
	global_load_dwordx4 v[176:179], v[10:11], off
	global_load_dwordx4 v[180:183], v[8:9], off
	v_or_b32_e32 v12, s13, v239
	v_mov_b64_e32 v[8:9], s[8:9]
	v_mad_u64_u32 v[10:11], s[16:17], v12, s18, v[8:9]
	v_or_b32_e32 v12, 1, v12
	v_lshl_add_u64 v[10:11], v[10:11], 0, v[6:7]
	v_mad_u64_u32 v[8:9], s[16:17], v12, s18, v[8:9]
	v_lshl_add_u64 v[6:7], v[8:9], 0, v[6:7]
	global_load_dwordx4 v[184:187], v[10:11], off
	global_load_dwordx4 v[188:191], v[6:7], off

.LBB0_471:
	s_cmp_lt_i32 s10, 0
	s_cbranch_scc1 .LBB0_462
	s_xor_b32 s8, s8, 1
	s_mul_i32 s0, s8, 0x9000
	v_add3_u32 v1, s0, v242, v243
	v_lshlrev_b32_e32 v0, 2, v241
	s_waitcnt vmcnt(0)
	ds_write_b128 v1, v[176:179]
	v_add3_u32 v1, s0, v244, v245
	ds_write_b128 v1, v[180:183]
	v_add3_u32 v0, s0, v0, v238
	s_mov_b32 s1, 0x5040100
	s_mov_b32 s0, 0x7060302
	v_perm_b32 v1, v188, v184, s1
	v_perm_b32 v2, v188, v184, s0
	v_add_u32_e32 v0, 0x3400, v0
	ds_write2_b32 v0, v1, v2 offset1:34
	v_perm_b32 v1, v189, v185, s1
	v_perm_b32 v2, v189, v185, s0
	ds_write2_b32 v0, v1, v2 offset0:68 offset1:102
	v_perm_b32 v1, v190, v186, s1
	v_perm_b32 v2, v190, v186, s0
	ds_write2_b32 v0, v1, v2 offset0:136 offset1:170
	v_perm_b32 v2, v191, v187, s0
	s_add_i32 s0, s10, -1
	s_cmp_gt_i32 s10, s11
	s_cselect_b32 s14, s0, -1
	v_perm_b32 v1, v191, v187, s1
	s_cmp_lt_i32 s14, 0
	ds_write2_b32 v0, v1, v2 offset0:204 offset1:238
	s_cbranch_scc1 .LBB0_474
	s_lshl_b32 s9, s14, 6
	v_add_u32_e32 v0, s9, v192
	s_movk_i32 s15, 0x1d00
	v_add_u32_e32 v2, s9, v240
	v_mad_i64_i32 v[0:1], s[0:1], v0, s15, v[212:213]
	v_mad_i64_i32 v[2:3], s[0:1], v2, s15, v[214:215]
	global_load_dwordx4 v[176:179], v[0:1], off
	global_load_dwordx4 v[180:183], v[2:3], off
	v_or_b32_e32 v2, s9, v239
	v_mad_u64_u32 v[0:1], s[0:1], v2, s15, v[210:211]
	v_or_b32_e32 v2, 1, v2
	v_mad_u64_u32 v[2:3], s[0:1], v2, s15, v[210:211]
	global_load_dwordx4 v[184:187], v[0:1], off
	global_load_dwordx4 v[188:191], v[2:3], off

.LBB0_488:
	s_mul_i32 s0, s8, 0x9000
	v_lshlrev_b32_e32 v32, 1, v108
	v_add3_u32 v106, s0, v118, v32
	v_mov_b32_e32 v128, v33
	ds_read_b128 v[32:35], v106 offset:4608
	ds_read_b128 v[36:39], v106
	ds_read_b128 v[130:133], v106 offset:32
	ds_read_b128 v[134:137], v106 offset:4640
	s_waitcnt lgkmcnt(2)
	v_mfma_f32_32x32x16_bf16 v[48:63], v[36:39], v[64:67], 0
	v_cmp_gt_i32_e32 vcc, 0, v126
	s_and_b64 vcc, exec, vcc
	v_mfma_f32_32x32x16_bf16 v[32:47], v[32:35], v[64:67], 0
	s_waitcnt lgkmcnt(1)
	v_mfma_f32_32x32x16_bf16 v[48:63], v[130:133], v[68:71], v[48:63]
	s_waitcnt lgkmcnt(0)
	v_mfma_f32_32x32x16_bf16 v[32:47], v[134:137], v[68:71], v[32:47]
	ds_read_b128 v[130:133], v106 offset:64
	ds_read_b128 v[134:137], v106 offset:4672
	s_waitcnt lgkmcnt(1)
	v_mfma_f32_32x32x16_bf16 v[48:63], v[130:133], v[72:75], v[48:63]
	s_waitcnt lgkmcnt(0)
	v_mfma_f32_32x32x16_bf16 v[32:47], v[134:137], v[72:75], v[32:47]
	ds_read_b128 v[130:133], v106 offset:96
	ds_read_b128 v[134:137], v106 offset:4704
	ds_read2_b32 v[106:107], v127 offset0:58 offset1:59
	ds_read2_b32 v[138:139], v127 offset0:2 offset1:3
	ds_read2_b32 v[140:141], v127 offset1:1
	s_waitcnt lgkmcnt(4)
	v_mfma_f32_32x32x16_bf16 v[48:63], v[130:133], v[76:79], v[48:63]
	ds_read2_b32 v[130:131], v127 offset0:18 offset1:19
	ds_read2_b32 v[132:133], v127 offset0:16 offset1:17
	s_waitcnt lgkmcnt(5)
	v_mfma_f32_32x32x16_bf16 v[32:47], v[134:137], v[76:79], v[32:47]
	s_nop 0
	s_nop 6
	s_waitcnt lgkmcnt(4)
	v_fmamk_f32 v107, v48, 0x3e38aa3b, v107
	v_fmac_f32_e32 v106, 0x3e38aa3b, v49
	ds_read2_b32 v[48:49], v127 offset0:56 offset1:57
	v_max3_f32 v129, v128, v107, v106
	ds_read2_b32 v[134:135], v127 offset0:10 offset1:11
	ds_read2_b32 v[136:137], v127 offset0:8 offset1:9
	s_waitcnt lgkmcnt(2)
	v_fmamk_f32 v49, v50, 0x3e38aa3b, v49
	v_fmac_f32_e32 v48, 0x3e38aa3b, v51
	ds_read2_b32 v[50:51], v127 offset0:50 offset1:51
	v_max3_f32 v129, v129, v49, v48
	s_waitcnt lgkmcnt(2)
	v_fmac_f32_e32 v134, 0x3e38aa3b, v41
	s_waitcnt lgkmcnt(1)
	v_fmac_f32_e32 v136, 0x3e38aa3b, v43
	v_fmac_f32_e32 v138, 0x3e38aa3b, v45
	s_waitcnt lgkmcnt(0)
	v_fmamk_f32 v51, v52, 0x3e38aa3b, v51
	v_fmac_f32_e32 v50, 0x3e38aa3b, v53
	ds_read2_b32 v[52:53], v127 offset0:48 offset1:49
	v_max3_f32 v129, v129, v51, v50
	v_fmac_f32_e32 v130, 0x3e38aa3b, v37
	v_fmac_f32_e32 v132, 0x3e38aa3b, v39
	v_fmac_f32_e32 v140, 0x3e38aa3b, v47
	s_waitcnt lgkmcnt(0)
	v_fmamk_f32 v53, v54, 0x3e38aa3b, v53
	v_fmac_f32_e32 v52, 0x3e38aa3b, v55
	ds_read2_b32 v[54:55], v127 offset0:42 offset1:43
	v_max3_f32 v129, v129, v53, v52
	s_waitcnt lgkmcnt(0)
	v_fmamk_f32 v55, v56, 0x3e38aa3b, v55
	v_fmac_f32_e32 v54, 0x3e38aa3b, v57
	ds_read2_b32 v[56:57], v127 offset0:40 offset1:41
	v_max3_f32 v129, v129, v55, v54
	s_waitcnt lgkmcnt(0)
	v_fmamk_f32 v57, v58, 0x3e38aa3b, v57
	v_fmac_f32_e32 v56, 0x3e38aa3b, v59
	ds_read2_b32 v[58:59], v127 offset0:34 offset1:35
	v_max3_f32 v129, v129, v57, v56
	s_waitcnt lgkmcnt(0)
	v_fmamk_f32 v59, v60, 0x3e38aa3b, v59
	v_fmac_f32_e32 v58, 0x3e38aa3b, v61
	ds_read2_b32 v[60:61], v127 offset0:32 offset1:33
	v_max3_f32 v129, v129, v59, v58
	s_waitcnt lgkmcnt(0)
	v_fmamk_f32 v61, v62, 0x3e38aa3b, v61
	v_fmac_f32_e32 v60, 0x3e38aa3b, v63
	ds_read2_b32 v[62:63], v127 offset0:26 offset1:27
	v_max3_f32 v129, v129, v61, v60
	s_waitcnt lgkmcnt(0)
	v_fmamk_f32 v63, v32, 0x3e38aa3b, v63
	v_fmac_f32_e32 v62, 0x3e38aa3b, v33
	ds_read2_b32 v[32:33], v127 offset0:24 offset1:25
	v_max3_f32 v129, v129, v63, v62
	s_waitcnt lgkmcnt(0)
	v_fmamk_f32 v142, v34, 0x3e38aa3b, v33
	v_fmac_f32_e32 v32, 0x3e38aa3b, v35
	v_max3_f32 v33, v129, v142, v32
	v_fmamk_f32 v129, v36, 0x3e38aa3b, v131
	v_max3_f32 v33, v33, v129, v130
	v_fmamk_f32 v131, v38, 0x3e38aa3b, v133
	v_max3_f32 v33, v33, v131, v132
	v_fmamk_f32 v133, v40, 0x3e38aa3b, v135
	v_max3_f32 v33, v33, v133, v134
	v_fmamk_f32 v135, v42, 0x3e38aa3b, v137
	v_max3_f32 v33, v33, v135, v136
	v_fmamk_f32 v137, v44, 0x3e38aa3b, v139
	v_max3_f32 v33, v33, v137, v138
	v_fmamk_f32 v139, v46, 0x3e38aa3b, v141
	v_max3_f32 v33, v33, v139, v140
	ds_bpermute_b32 v34, v119, v33
	s_waitcnt lgkmcnt(0)
	v_max_f32_e32 v34, v34, v34
	v_max_f32_e32 v33, v33, v34
	v_sub_f32_e32 v32, v32, v33
	v_sub_f32_e32 v40, v53, v33
	v_exp_f32_e32 v53, v32
	v_sub_f32_e32 v32, v129, v33
	v_sub_f32_e32 v43, v54, v33
	v_exp_f32_e32 v54, v32
	v_sub_f32_e32 v32, v130, v33
	v_sub_f32_e32 v42, v55, v33
	v_exp_f32_e32 v55, v32
	v_sub_f32_e32 v32, v131, v33
	v_sub_f32_e32 v45, v56, v33
	v_exp_f32_e32 v56, v32
	v_sub_f32_e32 v32, v132, v33
	v_sub_f32_e32 v44, v57, v33
	v_exp_f32_e32 v57, v32
	v_sub_f32_e32 v32, v133, v33
	v_sub_f32_e32 v47, v58, v33
	v_exp_f32_e32 v58, v32
	v_sub_f32_e32 v32, v134, v33
	v_sub_f32_e32 v46, v59, v33
	v_exp_f32_e32 v59, v32
	v_sub_f32_e32 v32, v135, v33
	v_sub_f32_e32 v36, v49, v33
	v_sub_f32_e32 v49, v60, v33
	v_exp_f32_e32 v60, v32
	v_sub_f32_e32 v32, v136, v33
	v_sub_f32_e32 v37, v48, v33
	v_sub_f32_e32 v48, v61, v33
	v_exp_f32_e32 v61, v32
	v_sub_f32_e32 v32, v137, v33
	v_sub_f32_e32 v38, v51, v33
	v_sub_f32_e32 v51, v62, v33
	v_exp_f32_e32 v62, v32
	v_sub_f32_e32 v32, v138, v33
	v_sub_f32_e32 v39, v50, v33
	v_sub_f32_e32 v50, v63, v33
	v_exp_f32_e32 v63, v32
	v_sub_f32_e32 v32, v139, v33
	v_sub_f32_e32 v35, v106, v33
	v_exp_f32_e32 v106, v32
	v_sub_f32_e32 v32, v140, v33
	v_add3_u32 v140, s0, v120, v121
	v_add_u32_e32 v144, 0x3000, v140
	v_add_u32_e32 v145, 0x4000, v140
	v_sub_f32_e32 v41, v52, v33
	v_sub_f32_e32 v52, v142, v33
	ds_read2_b64 v[132:135], v144 offset0:128 offset1:130
	ds_read2_b64 v[136:139], v144 offset0:132 offset1:134
	ds_read2_b64 v[140:143], v145 offset0:160 offset1:162
	v_sub_f32_e32 v128, v128, v33
	v_sub_f32_e32 v34, v107, v33
	v_exp_f32_e32 v34, v34
	v_exp_f32_e32 v35, v35
	v_exp_f32_e32 v36, v36
	v_exp_f32_e32 v37, v37
	v_exp_f32_e32 v38, v38
	v_exp_f32_e32 v39, v39
	v_exp_f32_e32 v40, v40
	v_exp_f32_e32 v41, v41
	v_exp_f32_e32 v107, v32
	v_exp_f32_e32 v32, v128
	v_cvt_pk_bf16_f32 v128, v34, v35
	v_cvt_pk_bf16_f32 v129, v36, v37
	v_cvt_pk_bf16_f32 v130, v38, v39
	v_pk_mul_f32 v[30:31], v[30:31], v[32:33] op_sel_hi:[1,0]
	v_pk_mul_f32 v[28:29], v[28:29], v[32:33] op_sel_hi:[1,0]
	v_pk_mul_f32 v[26:27], v[26:27], v[32:33] op_sel_hi:[1,0]
	v_pk_mul_f32 v[24:25], v[24:25], v[32:33] op_sel_hi:[1,0]
	v_pk_mul_f32 v[22:23], v[22:23], v[32:33] op_sel_hi:[1,0]
	v_pk_mul_f32 v[20:21], v[20:21], v[32:33] op_sel_hi:[1,0]
	v_pk_mul_f32 v[18:19], v[18:19], v[32:33] op_sel_hi:[1,0]
	v_pk_mul_f32 v[16:17], v[16:17], v[32:33] op_sel_hi:[1,0]
	v_cvt_pk_bf16_f32 v131, v40, v41
	v_pk_mul_f32 v[14:15], v[14:15], v[32:33] op_sel_hi:[1,0]
	v_pk_mul_f32 v[12:13], v[12:13], v[32:33] op_sel_hi:[1,0]
	v_pk_mul_f32 v[10:11], v[10:11], v[32:33] op_sel_hi:[1,0]
	v_pk_mul_f32 v[8:9], v[8:9], v[32:33] op_sel_hi:[1,0]
	v_pk_mul_f32 v[6:7], v[6:7], v[32:33] op_sel_hi:[1,0]
	v_pk_mul_f32 v[4:5], v[4:5], v[32:33] op_sel_hi:[1,0]
	v_pk_mul_f32 v[2:3], v[2:3], v[32:33] op_sel_hi:[1,0]
	v_pk_mul_f32 v[0:1], v[0:1], v[32:33] op_sel_hi:[1,0]
	s_waitcnt lgkmcnt(2)
	v_mfma_f32_32x32x16_bf16 v[16:31], v[132:135], v[128:131], v[16:31]
	ds_read2_b64 v[132:135], v145 offset0:164 offset1:166
	v_exp_f32_e32 v42, v42
	v_exp_f32_e32 v43, v43
	v_exp_f32_e32 v44, v44
	v_exp_f32_e32 v45, v45
	v_exp_f32_e32 v46, v46
	v_exp_f32_e32 v47, v47
	s_waitcnt lgkmcnt(1)
	v_mfma_f32_32x32x16_bf16 v[0:15], v[140:143], v[128:131], v[0:15]
	v_exp_f32_e32 v48, v48
	v_exp_f32_e32 v49, v49
	v_cvt_pk_bf16_f32 v128, v42, v43
	v_cvt_pk_bf16_f32 v129, v44, v45
	v_cvt_pk_bf16_f32 v130, v46, v47
	v_cvt_pk_bf16_f32 v131, v48, v49
	v_exp_f32_e32 v50, v50
	v_exp_f32_e32 v51, v51
	v_mfma_f32_32x32x16_bf16 v[16:31], v[136:139], v[128:131], v[16:31]
	v_exp_f32_e32 v52, v52
	s_waitcnt lgkmcnt(0)
	v_mfma_f32_32x32x16_bf16 v[0:15], v[132:135], v[128:131], v[0:15]
	ds_read2_b64 v[132:135], v144 offset0:136 offset1:138
	ds_read2_b64 v[136:139], v145 offset0:168 offset1:170
	v_cvt_pk_bf16_f32 v128, v50, v51
	v_cvt_pk_bf16_f32 v129, v52, v53
	v_cvt_pk_bf16_f32 v130, v54, v55
	v_cvt_pk_bf16_f32 v131, v56, v57
	s_nop 0
	s_nop 0
	s_waitcnt lgkmcnt(1)
	v_mfma_f32_32x32x16_bf16 v[16:31], v[132:135], v[128:131], v[16:31]
	s_waitcnt lgkmcnt(0)
	v_mfma_f32_32x32x16_bf16 v[0:15], v[136:139], v[128:131], v[0:15]
	ds_read2_b64 v[132:135], v144 offset0:140 offset1:142
	ds_read2_b64 v[136:139], v145 offset0:172 offset1:174
	v_cvt_pk_bf16_f32 v128, v58, v59
	v_cvt_pk_bf16_f32 v129, v60, v61
	v_cvt_pk_bf16_f32 v130, v62, v63
	v_cvt_pk_bf16_f32 v131, v106, v107
	s_nop 0
	s_nop 0
	s_waitcnt lgkmcnt(1)
	v_mfma_f32_32x32x16_bf16 v[16:31], v[132:135], v[128:131], v[16:31]
	s_waitcnt lgkmcnt(0)
	v_mfma_f32_32x32x16_bf16 v[0:15], v[136:139], v[128:131], v[0:15]
	s_cbranch_vccnz .LBB0_492
	s_xor_b32 s8, s8, 1
	s_mul_i32 s0, s8, 0x9000
	v_add3_u32 v129, s0, v114, v115
	v_lshlrev_b32_e32 v128, 2, v113
	s_waitcnt vmcnt(0)
	ds_write_b128 v129, v[80:83]
	v_add3_u32 v129, s0, v116, v117
	ds_write_b128 v129, v[84:87]
	v_add3_u32 v128, s0, v128, v112
	s_mov_b32 s1, 0x5040100
	s_mov_b32 s0, 0x7060302
	v_perm_b32 v129, v92, v88, s1
	v_perm_b32 v130, v92, v88, s0
	v_add_u32_e32 v128, 0x3400, v128
	ds_write2_b32 v128, v129, v130 offset1:34
	v_perm_b32 v129, v93, v89, s1
	v_perm_b32 v130, v93, v89, s0
	ds_write2_b32 v128, v129, v130 offset0:68 offset1:102
	v_perm_b32 v129, v94, v90, s1
	v_perm_b32 v130, v94, v90, s0
	ds_write2_b32 v128, v129, v130 offset0:136 offset1:170
	v_subrev_co_u32_e32 v126, vcc, 1, v126
	v_perm_b32 v129, v95, v91, s1
	v_perm_b32 v130, v95, v91, s0
	s_and_b64 vcc, exec, vcc
	ds_write2_b32 v128, v129, v130 offset0:204 offset1:238
	s_cbranch_vccnz .LBB0_491
	v_add_u32_e32 v90, 1, v123
	v_mad_i64_i32 v[80:81], s[0:1], v125, s17, v[102:103]
	v_mad_i64_i32 v[84:85], s[0:1], v124, s17, v[104:105]
	v_mad_u64_u32 v[88:89], s[0:1], v123, s17, v[100:101]
	v_mad_u64_u32 v[92:93], s[0:1], v90, s17, v[100:101]
	global_load_dwordx4 v[80:83], v[80:81], off offset:512
	s_nop 0
	global_load_dwordx4 v[84:87], v[84:85], off offset:512
	s_nop 0
	global_load_dwordx4 v[88:91], v[88:89], off offset:1024
	s_nop 0
	global_load_dwordx4 v[92:95], v[92:93], off offset:1024

.LBB0_496:
	s_and_b64 vcc, exec, s[8:9]
	s_cbranch_vccz .LBB0_715
	v_readlane_b32 s0, v253, 57
	v_readlane_b32 s9, v254, 45
	s_add_i32 s0, s0, s9
	s_ashr_i32 s10, s0, 5
	s_sub_i32 s8, 15, s10
	v_ashrrev_i32_e32 v0, 1, v198
	s_lshl_b32 s11, s8, 7
	v_and_b32_e32 v11, 0xffffffe0, v0
	v_and_b32_e32 v10, 31, v198
	v_add_u32_e32 v0, s11, v11
	s_mov_b64 s[12:13], 0x3e38aa3b
	v_or_b32_e32 v0, v0, v10
	s_lshl_b32 s0, s9, 9
	s_mov_b32 s1, s13
	v_readlane_b32 s12, v254, 3
	s_and_b32 s0, s0, 0x3800
	v_ashrrev_i32_e32 v1, 31, v0
	v_readlane_b32 s13, v254, 4
	s_waitcnt vmcnt(0)
	v_lshl_add_u64 v[130:131], v[0:1], 0, s[0:1]
	s_movk_i32 s76, 0x1d00
	v_mov_b64_e32 v[2:3], s[12:13]
	s_lshl_b32 s1, s9, 6
	v_lshrrev_b32_e32 v1, 2, v198
	v_mad_u64_u32 v[132:133], s[12:13], v130, s76, v[2:3]
	s_and_b32 s1, s1, 0xc0
	v_and_b32_e32 v1, 8, v1
	v_mov_b32_e32 v63, 0
	v_mad_i32_i24 v133, v131, s76, v133
	v_readfirstlane_b32 s83, v0
	s_cmp_gt_i32 s10, 15
	v_lshlrev_b32_e32 v128, 1, v1
	v_mov_b32_e32 v62, v63
	v_mov_b32_e32 v61, v63
	v_mov_b32_e32 v60, v63
	v_mov_b32_e32 v59, v63
	v_mov_b32_e32 v58, v63
	v_mov_b32_e32 v57, v63
	v_mov_b32_e32 v56, v63
	v_mov_b32_e32 v55, v63
	v_mov_b32_e32 v54, v63
	v_mov_b32_e32 v53, v63
	v_mov_b32_e32 v52, v63
	v_mov_b32_e32 v51, v63
	v_mov_b32_e32 v50, v63
	v_mov_b32_e32 v49, v63
	v_mov_b32_e32 v48, v63
	v_mov_b32_e32 v47, v63
	v_mov_b32_e32 v46, v63
	v_mov_b32_e32 v45, v63
	v_mov_b32_e32 v44, v63
	v_mov_b32_e32 v43, v63
	v_mov_b32_e32 v42, v63
	v_mov_b32_e32 v41, v63
	v_mov_b32_e32 v40, v63
	v_mov_b32_e32 v39, v63
	v_mov_b32_e32 v38, v63
	v_mov_b32_e32 v37, v63
	v_mov_b32_e32 v36, v63
	v_mov_b32_e32 v35, v63
	v_mov_b32_e32 v34, v63
	v_mov_b32_e32 v33, v63
	v_mov_b32_e32 v32, v63
	s_cbranch_scc1 .LBB0_513
	s_mov_b64 s[12:13], 0x3e38aa3b
	s_lshl_b32 s14, s1, 1
	s_mov_b32 s15, s13
	v_lshl_add_u64 v[0:1], v[132:133], 0, s[14:15]
	v_mov_b32_e32 v129, v193
	v_writelane_b32 v254, s1, 46
	v_lshl_add_u64 v[0:1], v[0:1], 0, v[128:129]
	s_mov_b64 s[12:13], 0x1400
	v_lshl_add_u64 v[2:3], v[0:1], 0, s[12:13]
	s_lshl_b32 s12, s8, 1
	s_mulk_i32 s0, 0x1d00
	v_readlane_b32 s8, v254, 3
	v_readlane_b32 s9, v254, 4
	s_add_u32 s0, s8, s0
	s_addc_u32 s1, s9, 0
	v_add_co_u32_e32 v0, vcc, 0x1000, v0
	s_add_u32 s8, s0, s14
	s_nop 0
	v_addc_co_u32_e32 v1, vcc, 0, v1, vcc
	s_addc_u32 s9, s1, 0
	global_load_dwordx4 v[96:99], v[0:1], off offset:1024
	global_load_dwordx4 v[100:103], v[2:3], off offset:32
	global_load_dwordx4 v[104:107], v[2:3], off offset:64
	global_load_dwordx4 v[108:111], v[2:3], off offset:96
	s_add_u32 s0, s8, 0x1600
	v_ashrrev_i32_e32 v0, 31, v198
	s_addc_u32 s1, s9, 0
	v_lshrrev_b32_e32 v0, 29, v0
	s_add_u32 s8, s8, 0x1800
	v_add_u32_e32 v0, v198, v0
	s_addc_u32 s9, s9, 0
	s_or_b32 s13, s11, 64
	v_ashrrev_i32_e32 v129, 3, v0
	v_and_b32_e32 v0, -8, v0
	v_sub_u32_e32 v33, v198, v0
	v_add_u32_e32 v0, s13, v129
	v_mov_b64_e32 v[6:7], s[0:1]
	v_mad_i64_i32 v[2:3], s[14:15], v0, s76, v[6:7]
	v_lshlrev_b32_e32 v0, 3, v33
	v_ashrrev_i32_e32 v1, 31, v0
	v_lshlrev_b64 v[0:1], 1, v[0:1]
	v_lshl_add_u64 v[2:3], v[2:3], 0, v[0:1]
	global_load_dwordx4 v[14:17], v[2:3], off
	v_add_u32_e32 v2, 0x100, v198
	v_ashrrev_i32_e32 v3, 31, v2
	v_lshrrev_b32_e32 v3, 29, v3
	v_add_u32_e32 v3, v2, v3
	v_ashrrev_i32_e32 v195, 3, v3
	v_and_b32_e32 v3, -8, v3
	v_sub_u32_e32 v34, v2, v3
	v_add_u32_e32 v2, s13, v195
	v_mad_i64_i32 v[4:5], s[14:15], v2, s76, v[6:7]
	v_lshlrev_b32_e32 v2, 3, v34
	v_ashrrev_i32_e32 v3, 31, v2
	v_lshlrev_b64 v[2:3], 1, v[2:3]
	v_lshl_add_u64 v[4:5], v[4:5], 0, v[2:3]
	global_load_dwordx4 v[18:21], v[4:5], off
	v_ashrrev_i32_e32 v4, 2, v198
	v_lshlrev_b32_e32 v199, 1, v10
	v_and_b32_e32 v30, -8, v4
	v_or_b32_e32 v26, s13, v199
	v_mov_b64_e32 v[8:9], s[8:9]
	v_ashrrev_i32_e32 v31, 31, v30
	v_mad_u64_u32 v[22:23], s[14:15], v26, s76, v[8:9]
	v_lshlrev_b64 v[4:5], 1, v[30:31]
	v_or_b32_e32 v26, 1, v26
	v_lshl_add_u64 v[22:23], v[22:23], 0, v[4:5]
	v_mad_u64_u32 v[26:27], s[14:15], v26, s76, v[8:9]
	global_load_dwordx4 v[22:25], v[22:23], off
	v_lshl_add_u64 v[26:27], v[26:27], 0, v[4:5]
	global_load_dwordx4 v[26:29], v[26:27], off
	s_movk_i32 s13, 0x90
	v_mul_lo_u32 v203, v129, s13
	v_lshlrev_b32_e32 v204, 4, v33
	v_mul_lo_u32 v202, v30, 34
	v_add_u32_e32 v30, v203, v204
	v_mul_lo_u32 v205, v195, s13
	v_lshlrev_b32_e32 v206, 4, v34
	s_waitcnt lgkmcnt(0)
	s_barrier
	v_lshlrev_b32_e32 v207, 2, v10
	s_mov_b32 s13, 0x7060302
	v_bfe_u32 v32, v198, 5, 1
	v_lshlrev_b32_e32 v210, 2, v32
	v_lshl_add_u64 v[136:137], s[0:1], 0, v[0:1]
	v_ashrrev_i32_e32 v13, 6, v198
	v_and_b32_e32 v12, 63, v198
	v_lshl_add_u64 v[134:135], s[8:9], 0, v[4:5]
	v_lshl_add_u64 v[138:139], s[0:1], 0, v[2:3]
	s_lshl_b32 s0, s10, 7
	v_mov_b32_e32 v141, 0
	s_mov_b32 s3, 0
	v_mul_u32_u24_e32 v209, 0x90, v10
	v_cmp_gt_u32_e64 s[8:9], 32, v12
	v_mul_u32_u24_e32 v211, 0x88, v10
	v_cmp_eq_u32_e64 s[18:19], 0, v12
	s_sub_i32 s82, 0x7ff, s0
	v_mov_b32_e32 v213, s12
	s_mov_b32 s2, 0
	v_mov_b32_e32 v33, v141
	v_mov_b32_e32 v34, v141
	v_mov_b32_e32 v35, v141
	v_mov_b32_e32 v36, v141
	v_mov_b32_e32 v37, v141
	v_mov_b32_e32 v38, v141
	v_mov_b32_e32 v39, v141
	v_mov_b32_e32 v40, v141
	v_mov_b32_e32 v41, v141
	v_mov_b32_e32 v42, v141
	v_mov_b32_e32 v43, v141
	v_mov_b32_e32 v44, v141
	v_mov_b32_e32 v45, v141
	v_mov_b32_e32 v46, v141
	v_mov_b32_e32 v47, v141
	v_mov_b32_e32 v48, v141
	v_mov_b32_e32 v49, v141
	v_mov_b32_e32 v50, v141
	v_mov_b32_e32 v51, v141
	s_waitcnt vmcnt(3)
	ds_write_b128 v30, v[14:17]
	v_add_u32_e32 v14, v205, v206
	v_mov_b32_e32 v52, v141
	v_mov_b32_e32 v53, v141
	v_mov_b32_e32 v54, v141
	v_mov_b32_e32 v55, v141
	v_mov_b32_e32 v56, v141
	v_mov_b32_e32 v57, v141
	v_mov_b32_e32 v58, v141
	v_mov_b32_e32 v59, v141
	v_mov_b32_e32 v60, v141
	v_mov_b32_e32 v61, v141
	v_mov_b32_e32 v62, v141
	v_mov_b32_e32 v63, v141
	s_waitcnt vmcnt(2)
	ds_write_b128 v14, v[18:21]
	v_lshl_add_u32 v14, v202, 2, v207
	v_add_u32_e32 v14, 0x3400, v14
	s_waitcnt vmcnt(1)
	v_and_b32_e32 v15, 0xffff, v22
	s_waitcnt vmcnt(0)
	v_lshl_or_b32 v15, v26, 16, v15
	v_perm_b32 v16, v26, v22, s13
	ds_write2_b32 v14, v15, v16 offset1:34
	v_and_b32_e32 v15, 0xffff, v23
	v_lshl_or_b32 v15, v27, 16, v15
	v_perm_b32 v16, v27, v23, s13
	ds_write2_b32 v14, v15, v16 offset0:68 offset1:102
	v_and_b32_e32 v15, 0xffff, v24
	v_lshl_or_b32 v15, v28, 16, v15
	v_perm_b32 v16, v28, v24, s13
	ds_write2_b32 v14, v15, v16 offset0:136 offset1:170
	v_and_b32_e32 v15, 0xffff, v25
	v_lshl_or_b32 v15, v29, 16, v15
	v_perm_b32 v16, v29, v25, s13
	ds_write2_b32 v14, v15, v16 offset0:204 offset1:238
	v_add_u32_e32 v14, s11, v129
	v_mad_i64_i32 v[14:15], s[14:15], v14, s76, v[6:7]
	v_lshl_add_u64 v[14:15], v[14:15], 0, v[0:1]
	global_load_dwordx4 v[112:115], v[14:15], off
	v_add_u32_e32 v14, s11, v195
	v_mad_i64_i32 v[6:7], s[14:15], v14, s76, v[6:7]
	v_lshl_add_u64 v[6:7], v[6:7], 0, v[2:3]
	v_or_b32_e32 v14, s11, v199
	global_load_dwordx4 v[116:119], v[6:7], off
	v_mad_u64_u32 v[6:7], s[14:15], v14, s76, v[8:9]
	v_lshl_add_u64 v[6:7], v[6:7], 0, v[4:5]
	global_load_dwordx4 v[120:123], v[6:7], off
	v_or_b32_e32 v6, 1, v14
	v_mad_u64_u32 v[6:7], s[14:15], v6, s76, v[8:9]
	v_lshl_add_u64 v[6:7], v[6:7], 0, v[4:5]
	global_load_dwordx4 v[124:127], v[6:7], off
	v_add_u32_e32 v0, v11, v10
	s_add_i32 s14, s83, 31
	v_mov_b32_e32 v6, 0x11490
	v_lshlrev_b32_e32 v4, 3, v32
	v_sub_u32_e32 v0, v0, v210
	v_lshl_add_u32 v208, v13, 2, v6
	v_subrev_u32_e32 v214, 64, v0
	s_mov_b64 s[10:11], 0
	v_lshlrev_b32_e32 v212, 1, v4
	v_mov_b32_e32 v32, v141
	v_writelane_b32 v254, s14, 48
	s_waitcnt lgkmcnt(0)
	s_barrier
	s_branch .LBB0_500

.LBB0_509:
	s_or_b64 exec, exec, s[0:1]
	s_xor_b32 s2, s2, 1
	s_mul_i32 s0, s2, 0x9000
	v_add3_u32 v1, s0, v203, v204
	v_lshlrev_b32_e32 v0, 2, v202
	s_waitcnt vmcnt(0)
	ds_write_b128 v1, v[112:115]
	v_add3_u32 v1, s0, v205, v206
	ds_write_b128 v1, v[116:119]
	v_add3_u32 v0, s0, v0, v207
	s_mov_b32 s1, 0x5040100
	s_mov_b32 s0, 0x7060302
	v_perm_b32 v1, v124, v120, s1
	v_perm_b32 v2, v124, v120, s0
	v_add_u32_e32 v0, 0x3400, v0
	ds_write2_b32 v0, v1, v2 offset1:34
	v_perm_b32 v1, v125, v121, s1
	v_perm_b32 v2, v125, v121, s0
	ds_write2_b32 v0, v1, v2 offset0:68 offset1:102
	v_perm_b32 v1, v126, v122, s1
	v_perm_b32 v2, v126, v122, s0
	ds_write2_b32 v0, v1, v2 offset0:136 offset1:170
	v_subrev_co_u32_e32 v213, vcc, 1, v213
	v_perm_b32 v1, v127, v123, s1
	v_perm_b32 v2, v127, v123, s0
	s_and_b64 vcc, exec, vcc
	ds_write2_b32 v0, v1, v2 offset0:204 offset1:238
	s_cbranch_vccnz .LBB0_499
	v_add_u32_e32 v0, s82, v129
	v_add_u32_e32 v2, s82, v195
	v_add_u32_e32 v0, 0xffffff41, v0
	v_add_u32_e32 v2, 0xffffff41, v2
	v_mad_i64_i32 v[0:1], s[0:1], v0, s76, v[136:137]
	v_mad_i64_i32 v[2:3], s[0:1], v2, s76, v[138:139]
	global_load_dwordx4 v[112:115], v[0:1], off
	global_load_dwordx4 v[116:119], v[2:3], off
	v_add_u32_e32 v2, s82, v199
	v_add_u32_e32 v0, 0xffffff41, v2
	v_mad_u64_u32 v[0:1], s[0:1], v0, s76, v[134:135]
	v_add_u32_e32 v2, 0xffffff42, v2
	v_mad_u64_u32 v[2:3], s[0:1], v2, s76, v[134:135]
	global_load_dwordx4 v[120:123], v[0:1], off
	global_load_dwordx4 v[124:127], v[2:3], off
	s_branch .LBB0_499

.LBB0_556:
	s_or_b64 exec, exec, s[0:1]
	v_cmp_lt_i32_e64 s[0:1], -1, v192
	v_lshlrev_b32_e32 v32, 3, v39
	s_waitcnt vmcnt(0)
	v_lshl_add_u64 v[34:35], v[192:193], 2, s[40:41]
	v_mov_b32_e32 v4, 0
	v_mov_b32_e32 v0, 0
	v_mov_b32_e32 v1, 0
	v_mov_b32_e32 v2, 0
	v_mov_b32_e32 v3, 0
	s_and_saveexec_b64 s[28:29], s[0:1]
	s_cbranch_execz .LBB0_559
	v_mad_i64_i32 v[0:1], s[30:31], v32, s78, v[34:35]
	global_load_dwordx4 v[0:3], v[0:1], off
	s_and_b64 vcc, exec, s[74:75]
	s_cbranch_vccnz .LBB0_559
	v_ashrrev_i32_e32 v33, 31, v32
	v_lshl_add_u64 v[6:7], v[32:33], 2, s[86:87]
	global_load_dword v50, v[6:7], off
.LBB0_559:
	s_or_b64 exec, exec, s[28:29]
	v_mov_b32_e32 v5, 0
	v_mov_b32_e32 v6, 0
	v_mov_b32_e32 v7, 0
	s_and_saveexec_b64 s[28:29], s[0:1]
	s_cbranch_execz .LBB0_562
	v_or_b32_e32 v8, 1, v32
	v_mad_i64_i32 v[4:5], s[30:31], v8, s78, v[34:35]
	global_load_dwordx4 v[4:7], v[4:5], off
	s_and_b64 vcc, exec, s[74:75]
	s_cbranch_vccnz .LBB0_562
	v_ashrrev_i32_e32 v9, 31, v8
	v_lshl_add_u64 v[8:9], v[8:9], 2, s[86:87]
	global_load_dword v51, v[8:9], off
.LBB0_562:
	s_or_b64 exec, exec, s[28:29]
	v_mov_b32_e32 v8, 0
	v_mov_b32_e32 v12, 0
	v_mov_b32_e32 v13, 0
	v_mov_b32_e32 v14, 0
	v_mov_b32_e32 v15, 0
	s_and_saveexec_b64 s[28:29], s[0:1]
	s_cbranch_execz .LBB0_565
	v_or_b32_e32 v10, 2, v32
	v_mad_i64_i32 v[12:13], s[30:31], v10, s78, v[34:35]
	global_load_dwordx4 v[12:15], v[12:13], off
	s_and_b64 vcc, exec, s[74:75]
	s_cbranch_vccnz .LBB0_565
	v_ashrrev_i32_e32 v11, 31, v10
	v_lshl_add_u64 v[10:11], v[10:11], 2, s[86:87]
	global_load_dword v52, v[10:11], off
.LBB0_565:
	s_or_b64 exec, exec, s[28:29]
	v_mov_b32_e32 v9, 0
	v_mov_b32_e32 v10, 0
	v_mov_b32_e32 v11, 0
	s_and_saveexec_b64 s[28:29], s[0:1]
	s_cbranch_execz .LBB0_568
	v_or_b32_e32 v16, 3, v32
	v_mad_i64_i32 v[8:9], s[30:31], v16, s78, v[34:35]
	global_load_dwordx4 v[8:11], v[8:9], off
	s_and_b64 vcc, exec, s[74:75]
	s_cbranch_vccnz .LBB0_568
	v_ashrrev_i32_e32 v17, 31, v16
	v_lshl_add_u64 v[16:17], v[16:17], 2, s[86:87]
	global_load_dword v53, v[16:17], off
.LBB0_568:
	s_or_b64 exec, exec, s[28:29]
	v_mov_b32_e32 v16, 0
	v_mov_b32_e32 v20, 0
	v_mov_b32_e32 v21, 0
	v_mov_b32_e32 v22, 0
	v_mov_b32_e32 v23, 0
	s_and_saveexec_b64 s[28:29], s[0:1]
	s_cbranch_execz .LBB0_571
	v_or_b32_e32 v18, 4, v32
	v_mad_i64_i32 v[20:21], s[30:31], v18, s78, v[34:35]
	global_load_dwordx4 v[20:23], v[20:21], off
	s_and_b64 vcc, exec, s[74:75]
	s_cbranch_vccnz .LBB0_571
	v_ashrrev_i32_e32 v19, 31, v18
	v_lshl_add_u64 v[18:19], v[18:19], 2, s[86:87]
	global_load_dword v54, v[18:19], off
.LBB0_571:
	s_or_b64 exec, exec, s[28:29]
	v_mov_b32_e32 v17, 0
	v_mov_b32_e32 v18, 0
	v_mov_b32_e32 v19, 0
	s_and_saveexec_b64 s[28:29], s[0:1]
	s_cbranch_execz .LBB0_574
	v_or_b32_e32 v24, 5, v32
	v_mad_i64_i32 v[16:17], s[30:31], v24, s78, v[34:35]
	global_load_dwordx4 v[16:19], v[16:17], off
	s_and_b64 vcc, exec, s[74:75]
	s_cbranch_vccnz .LBB0_574
	v_ashrrev_i32_e32 v25, 31, v24
	v_lshl_add_u64 v[24:25], v[24:25], 2, s[86:87]
	global_load_dword v55, v[24:25], off
.LBB0_574:
	s_or_b64 exec, exec, s[28:29]
	v_mov_b32_e32 v24, 0
	v_mov_b32_e32 v28, 0
	v_mov_b32_e32 v29, 0
	v_mov_b32_e32 v30, 0
	v_mov_b32_e32 v31, 0
	s_and_saveexec_b64 s[28:29], s[0:1]
	s_cbranch_execz .LBB0_577
	v_or_b32_e32 v26, 6, v32
	v_mad_i64_i32 v[28:29], s[30:31], v26, s78, v[34:35]
	global_load_dwordx4 v[28:31], v[28:29], off
	s_and_b64 vcc, exec, s[74:75]
	s_cbranch_vccnz .LBB0_577
	v_ashrrev_i32_e32 v27, 31, v26
	v_lshl_add_u64 v[26:27], v[26:27], 2, s[86:87]
	global_load_dword v56, v[26:27], off
.LBB0_577:
	s_or_b64 exec, exec, s[28:29]
	v_mov_b32_e32 v25, 0
	v_mov_b32_e32 v26, 0
	v_mov_b32_e32 v27, 0
	s_and_saveexec_b64 s[28:29], s[0:1]
	s_cbranch_execz .LBB0_541
	v_or_b32_e32 v32, 7, v32
	v_mad_i64_i32 v[24:25], s[0:1], v32, s78, v[34:35]
	global_load_dwordx4 v[24:27], v[24:25], off
	s_and_b64 vcc, exec, s[74:75]
	s_cbranch_vccnz .LBB0_541
	v_ashrrev_i32_e32 v33, 31, v32
	v_lshl_add_u64 v[32:33], v[32:33], 2, s[86:87]
	global_load_dword v57, v[32:33], off
	s_waitcnt vmcnt(0)
	v_mul_f32_e32 v2, v2, v50
	v_mul_f32_e32 v3, v3, v50
	v_mul_f32_e32 v0, v0, v50
	v_mul_f32_e32 v1, v1, v50
	v_mul_f32_e32 v6, v6, v51
	v_mul_f32_e32 v7, v7, v51
	v_mul_f32_e32 v4, v4, v51
	v_mul_f32_e32 v5, v5, v51
	v_mul_f32_e32 v14, v14, v52
	v_mul_f32_e32 v15, v15, v52
	v_mul_f32_e32 v12, v12, v52
	v_mul_f32_e32 v13, v13, v52
	v_mul_f32_e32 v10, v10, v53
	v_mul_f32_e32 v11, v11, v53
	v_mul_f32_e32 v8, v8, v53
	v_mul_f32_e32 v9, v9, v53
	v_mul_f32_e32 v22, v22, v54
	v_mul_f32_e32 v23, v23, v54
	v_mul_f32_e32 v20, v20, v54
	v_mul_f32_e32 v21, v21, v54
	v_mul_f32_e32 v18, v18, v55
	v_mul_f32_e32 v19, v19, v55
	v_mul_f32_e32 v16, v16, v55
	v_mul_f32_e32 v17, v17, v55
	v_mul_f32_e32 v30, v30, v56
	v_mul_f32_e32 v31, v31, v56
	v_mul_f32_e32 v28, v28, v56
	v_mul_f32_e32 v29, v29, v56
	v_mul_f32_e32 v26, v26, v57
	v_mul_f32_e32 v27, v27, v57
	v_mul_f32_e32 v24, v24, v57
	v_mul_f32_e32 v25, v25, v57
	s_branch .LBB0_541

.LBB0_583:
	v_mul_hi_i32 v0, v34, s54
	v_lshrrev_b32_e32 v1, 31, v0
	v_ashrrev_i32_e32 v0, 4, v0
	v_add_u32_e32 v2, v0, v1
	s_movk_i32 s0, 0xffa0
	v_mad_u64_u32 v[0:1], s[0:1], v2, s0, v[34:35]
	s_movk_i32 s0, 0xfe80
	s_nop 0
	v_mad_u64_u32 v[36:37], s[0:1], v2, s0, v[32:33]
	v_lshlrev_b32_e32 v38, 3, v2
	v_mov_b32_e32 v37, v193
	v_cmp_lt_i32_e64 s[0:1], -1, v0
	v_lshl_add_u64 v[40:41], v[36:37], 2, s[42:43]
	v_mov_b32_e32 v0, 0
	v_ashrrev_i32_e32 v39, 31, v38
	v_mov_b32_e32 v4, 0
	v_mov_b32_e32 v5, 0
	v_mov_b32_e32 v6, 0
	v_mov_b32_e32 v7, 0
	s_and_saveexec_b64 s[28:29], s[0:1]
	s_cbranch_execz .LBB0_586
	v_mad_i64_i32 v[2:3], s[34:35], v38, s33, v[40:41]
	global_load_dwordx4 v[4:7], v[2:3], off
	s_and_b64 vcc, exec, s[4:5]
	s_cbranch_vccnz .LBB0_586
	v_lshl_add_u64 v[2:3], v[38:39], 2, s[90:91]
	global_load_dword v50, v[2:3], off offset:1024
.LBB0_586:
	s_or_b64 exec, exec, s[28:29]
	v_mov_b32_e32 v1, 0
	v_mov_b32_e32 v2, 0
	v_mov_b32_e32 v3, 0
	s_and_saveexec_b64 s[28:29], s[0:1]
	s_cbranch_execz .LBB0_589
	v_or_b32_e32 v0, 1, v38
	v_mad_i64_i32 v[0:1], s[34:35], v0, s33, v[40:41]
	global_load_dwordx4 v[0:3], v[0:1], off
	s_and_b64 vcc, exec, s[4:5]
	s_cbranch_vccnz .LBB0_589
	v_lshl_add_u64 v[8:9], v[38:39], 2, s[90:91]
	global_load_dword v51, v[8:9], off offset:1028
.LBB0_589:
	s_or_b64 exec, exec, s[28:29]
	v_mov_b32_e32 v8, 0
	v_mov_b32_e32 v12, 0
	v_mov_b32_e32 v13, 0
	v_mov_b32_e32 v14, 0
	v_mov_b32_e32 v15, 0
	s_and_saveexec_b64 s[28:29], s[0:1]
	s_cbranch_execz .LBB0_592
	v_or_b32_e32 v9, 2, v38
	v_mad_i64_i32 v[10:11], s[34:35], v9, s33, v[40:41]
	global_load_dwordx4 v[12:15], v[10:11], off
	s_and_b64 vcc, exec, s[4:5]
	s_cbranch_vccnz .LBB0_592
	v_lshl_add_u64 v[10:11], v[38:39], 2, s[90:91]
	global_load_dword v52, v[10:11], off offset:1032
.LBB0_592:
	s_or_b64 exec, exec, s[28:29]
	v_mov_b32_e32 v9, 0
	v_mov_b32_e32 v10, 0
	v_mov_b32_e32 v11, 0
	s_and_saveexec_b64 s[28:29], s[0:1]
	s_cbranch_execz .LBB0_595
	v_or_b32_e32 v8, 3, v38
	v_mad_i64_i32 v[8:9], s[34:35], v8, s33, v[40:41]
	global_load_dwordx4 v[8:11], v[8:9], off
	s_and_b64 vcc, exec, s[4:5]
	s_cbranch_vccnz .LBB0_595
	v_lshl_add_u64 v[16:17], v[38:39], 2, s[90:91]
	global_load_dword v53, v[16:17], off offset:1036
.LBB0_595:
	s_or_b64 exec, exec, s[28:29]
	v_mov_b32_e32 v16, 0
	v_mov_b32_e32 v20, 0
	v_mov_b32_e32 v21, 0
	v_mov_b32_e32 v22, 0
	v_mov_b32_e32 v23, 0
	s_and_saveexec_b64 s[28:29], s[0:1]
	s_cbranch_execz .LBB0_598
	v_or_b32_e32 v17, 4, v38
	v_mad_i64_i32 v[18:19], s[34:35], v17, s33, v[40:41]
	global_load_dwordx4 v[20:23], v[18:19], off
	s_and_b64 vcc, exec, s[4:5]
	s_cbranch_vccnz .LBB0_598
	v_lshl_add_u64 v[18:19], v[38:39], 2, s[90:91]
	global_load_dword v54, v[18:19], off offset:1040
.LBB0_598:
	s_or_b64 exec, exec, s[28:29]
	v_mov_b32_e32 v17, 0
	v_mov_b32_e32 v18, 0
	v_mov_b32_e32 v19, 0
	s_and_saveexec_b64 s[28:29], s[0:1]
	s_cbranch_execz .LBB0_601
	v_or_b32_e32 v16, 5, v38
	v_mad_i64_i32 v[16:17], s[34:35], v16, s33, v[40:41]
	global_load_dwordx4 v[16:19], v[16:17], off
	s_and_b64 vcc, exec, s[4:5]
	s_cbranch_vccnz .LBB0_601
	v_lshl_add_u64 v[24:25], v[38:39], 2, s[90:91]
	global_load_dword v55, v[24:25], off offset:1044
.LBB0_601:
	s_or_b64 exec, exec, s[28:29]
	v_mov_b32_e32 v24, 0
	v_mov_b32_e32 v28, 0
	v_mov_b32_e32 v29, 0
	v_mov_b32_e32 v30, 0
	v_mov_b32_e32 v31, 0
	s_and_saveexec_b64 s[28:29], s[0:1]
	s_cbranch_execz .LBB0_604
	v_or_b32_e32 v25, 6, v38
	v_mad_i64_i32 v[26:27], s[34:35], v25, s33, v[40:41]
	global_load_dwordx4 v[28:31], v[26:27], off
	s_and_b64 vcc, exec, s[4:5]
	s_cbranch_vccnz .LBB0_604
	v_lshl_add_u64 v[26:27], v[38:39], 2, s[90:91]
	global_load_dword v56, v[26:27], off offset:1048
.LBB0_604:
	s_or_b64 exec, exec, s[28:29]
	v_mov_b32_e32 v25, 0
	v_mov_b32_e32 v26, 0
	v_mov_b32_e32 v27, 0
	s_and_saveexec_b64 s[28:29], s[0:1]
	s_cbranch_execz .LBB0_582
	v_or_b32_e32 v24, 7, v38
	v_mad_i64_i32 v[24:25], s[0:1], v24, s33, v[40:41]
	global_load_dwordx4 v[24:27], v[24:25], off
	s_and_b64 vcc, exec, s[4:5]
	s_cbranch_vccnz .LBB0_582
	v_lshl_add_u64 v[40:41], v[38:39], 2, s[90:91]
	global_load_dword v57, v[40:41], off offset:1052
	s_waitcnt vmcnt(0)
	v_mul_f32_e32 v6, v6, v50
	v_mul_f32_e32 v7, v7, v50
	v_mul_f32_e32 v4, v4, v50
	v_mul_f32_e32 v5, v5, v50
	v_mul_f32_e32 v2, v2, v51
	v_mul_f32_e32 v3, v3, v51
	v_mul_f32_e32 v0, v0, v51
	v_mul_f32_e32 v1, v1, v51
	v_mul_f32_e32 v14, v14, v52
	v_mul_f32_e32 v15, v15, v52
	v_mul_f32_e32 v12, v12, v52
	v_mul_f32_e32 v13, v13, v52
	v_mul_f32_e32 v10, v10, v53
	v_mul_f32_e32 v11, v11, v53
	v_mul_f32_e32 v8, v8, v53
	v_mul_f32_e32 v9, v9, v53
	v_mul_f32_e32 v22, v22, v54
	v_mul_f32_e32 v23, v23, v54
	v_mul_f32_e32 v20, v20, v54
	v_mul_f32_e32 v21, v21, v54
	v_mul_f32_e32 v18, v18, v55
	v_mul_f32_e32 v19, v19, v55
	v_mul_f32_e32 v16, v16, v55
	v_mul_f32_e32 v17, v17, v55
	v_mul_f32_e32 v30, v30, v56
	v_mul_f32_e32 v31, v31, v56
	v_mul_f32_e32 v28, v28, v56
	v_mul_f32_e32 v29, v29, v56
	v_mul_f32_e32 v26, v26, v57
	v_mul_f32_e32 v27, v27, v57
	v_mul_f32_e32 v24, v24, v57
	v_mul_f32_e32 v25, v25, v57
	s_branch .LBB0_582

.LBB0_610:
	v_ashrrev_i32_e32 v0, 31, v37
	v_lshrrev_b32_e32 v0, 25, v0
	v_add_u32_e32 v0, v37, v0
	v_ashrrev_i32_e32 v1, 7, v0
	v_and_b32_e32 v0, 0xffffff80, v0
	v_lshlrev_b32_e32 v2, 9, v1
	v_sub_u32_e32 v0, v37, v0
	v_sub_u32_e32 v192, v36, v2
	v_lshlrev_b32_e32 v32, 3, v1
	v_cmp_lt_i32_e64 s[0:1], -1, v0
	s_waitcnt vmcnt(0)
	v_lshl_add_u64 v[34:35], v[192:193], 2, s[44:45]
	v_mov_b32_e32 v4, 0
	v_ashrrev_i32_e32 v33, 31, v32
	v_mov_b32_e32 v0, 0
	v_mov_b32_e32 v1, 0
	v_mov_b32_e32 v2, 0
	v_mov_b32_e32 v3, 0
	s_and_saveexec_b64 s[28:29], s[0:1]
	s_cbranch_execz .LBB0_613
	v_lshlrev_b64 v[0:1], 11, v[32:33]
	v_lshl_add_u64 v[0:1], v[34:35], 0, v[0:1]
	global_load_dwordx4 v[0:3], v[0:1], off
	s_and_b64 vcc, exec, s[6:7]
	s_cbranch_vccnz .LBB0_613
	v_lshl_add_u64 v[6:7], v[32:33], 2, s[92:93]
	global_load_dword v50, v[6:7], off offset:512
.LBB0_613:
	s_or_b64 exec, exec, s[28:29]
	v_mov_b32_e32 v5, 0
	v_mov_b32_e32 v6, 0
	v_mov_b32_e32 v7, 0
	s_and_saveexec_b64 s[28:29], s[0:1]
	s_cbranch_execz .LBB0_616
	v_or_b32_e32 v4, 1, v32
	v_ashrrev_i32_e32 v5, 31, v4
	v_lshlrev_b64 v[4:5], 11, v[4:5]
	v_lshl_add_u64 v[4:5], v[34:35], 0, v[4:5]
	global_load_dwordx4 v[4:7], v[4:5], off
	s_and_b64 vcc, exec, s[6:7]
	s_cbranch_vccnz .LBB0_616
	v_lshl_add_u64 v[8:9], v[32:33], 2, s[92:93]
	global_load_dword v51, v[8:9], off offset:516
.LBB0_616:
	s_or_b64 exec, exec, s[28:29]
	v_mov_b32_e32 v8, 0
	v_mov_b32_e32 v12, 0
	v_mov_b32_e32 v13, 0
	v_mov_b32_e32 v14, 0
	v_mov_b32_e32 v15, 0
	s_and_saveexec_b64 s[28:29], s[0:1]
	s_cbranch_execz .LBB0_619
	v_or_b32_e32 v10, 2, v32
	v_ashrrev_i32_e32 v11, 31, v10
	v_lshlrev_b64 v[10:11], 11, v[10:11]
	v_lshl_add_u64 v[10:11], v[34:35], 0, v[10:11]
	global_load_dwordx4 v[12:15], v[10:11], off
	s_and_b64 vcc, exec, s[6:7]
	s_cbranch_vccnz .LBB0_619
	v_lshl_add_u64 v[10:11], v[32:33], 2, s[92:93]
	global_load_dword v52, v[10:11], off offset:520
.LBB0_619:
	s_or_b64 exec, exec, s[28:29]
	v_mov_b32_e32 v9, 0
	v_mov_b32_e32 v10, 0
	v_mov_b32_e32 v11, 0
	s_and_saveexec_b64 s[28:29], s[0:1]
	s_cbranch_execz .LBB0_622
	v_or_b32_e32 v8, 3, v32
	v_ashrrev_i32_e32 v9, 31, v8
	v_lshlrev_b64 v[8:9], 11, v[8:9]
	v_lshl_add_u64 v[8:9], v[34:35], 0, v[8:9]
	global_load_dwordx4 v[8:11], v[8:9], off
	s_and_b64 vcc, exec, s[6:7]
	s_cbranch_vccnz .LBB0_622
	v_lshl_add_u64 v[16:17], v[32:33], 2, s[92:93]
	global_load_dword v53, v[16:17], off offset:524
.LBB0_622:
	s_or_b64 exec, exec, s[28:29]
	v_mov_b32_e32 v16, 0
	v_mov_b32_e32 v20, 0
	v_mov_b32_e32 v21, 0
	v_mov_b32_e32 v22, 0
	v_mov_b32_e32 v23, 0
	s_and_saveexec_b64 s[28:29], s[0:1]
	s_cbranch_execz .LBB0_625
	v_or_b32_e32 v18, 4, v32
	v_ashrrev_i32_e32 v19, 31, v18
	v_lshlrev_b64 v[18:19], 11, v[18:19]
	v_lshl_add_u64 v[18:19], v[34:35], 0, v[18:19]
	global_load_dwordx4 v[20:23], v[18:19], off
	s_and_b64 vcc, exec, s[6:7]
	s_cbranch_vccnz .LBB0_625
	v_lshl_add_u64 v[18:19], v[32:33], 2, s[92:93]
	global_load_dword v54, v[18:19], off offset:528
.LBB0_625:
	s_or_b64 exec, exec, s[28:29]
	v_mov_b32_e32 v17, 0
	v_mov_b32_e32 v18, 0
	v_mov_b32_e32 v19, 0
	s_and_saveexec_b64 s[28:29], s[0:1]
	s_cbranch_execz .LBB0_628
	v_or_b32_e32 v16, 5, v32
	v_ashrrev_i32_e32 v17, 31, v16
	v_lshlrev_b64 v[16:17], 11, v[16:17]
	v_lshl_add_u64 v[16:17], v[34:35], 0, v[16:17]
	global_load_dwordx4 v[16:19], v[16:17], off
	s_and_b64 vcc, exec, s[6:7]
	s_cbranch_vccnz .LBB0_628
	v_lshl_add_u64 v[24:25], v[32:33], 2, s[92:93]
	global_load_dword v55, v[24:25], off offset:532
.LBB0_628:
	s_or_b64 exec, exec, s[28:29]
	v_mov_b32_e32 v24, 0
	v_mov_b32_e32 v28, 0
	v_mov_b32_e32 v29, 0
	v_mov_b32_e32 v30, 0
	v_mov_b32_e32 v31, 0
	s_and_saveexec_b64 s[28:29], s[0:1]
	s_cbranch_execz .LBB0_631
	v_or_b32_e32 v26, 6, v32
	v_ashrrev_i32_e32 v27, 31, v26
	v_lshlrev_b64 v[26:27], 11, v[26:27]
	v_lshl_add_u64 v[26:27], v[34:35], 0, v[26:27]
	global_load_dwordx4 v[28:31], v[26:27], off
	s_and_b64 vcc, exec, s[6:7]
	s_cbranch_vccnz .LBB0_631
	v_lshl_add_u64 v[26:27], v[32:33], 2, s[92:93]
	global_load_dword v56, v[26:27], off offset:536
.LBB0_631:
	s_or_b64 exec, exec, s[28:29]
	v_mov_b32_e32 v25, 0
	v_mov_b32_e32 v26, 0
	v_mov_b32_e32 v27, 0
	s_and_saveexec_b64 s[28:29], s[0:1]
	s_cbranch_execz .LBB0_609
	v_or_b32_e32 v24, 7, v32
	v_ashrrev_i32_e32 v25, 31, v24
	v_lshlrev_b64 v[24:25], 11, v[24:25]
	v_lshl_add_u64 v[24:25], v[34:35], 0, v[24:25]
	global_load_dwordx4 v[24:27], v[24:25], off
	s_and_b64 vcc, exec, s[6:7]
	s_cbranch_vccnz .LBB0_609
	v_lshl_add_u64 v[34:35], v[32:33], 2, s[92:93]
	global_load_dword v57, v[34:35], off offset:540
	s_waitcnt vmcnt(0)
	v_mul_f32_e32 v2, v2, v50
	v_mul_f32_e32 v3, v3, v50
	v_mul_f32_e32 v0, v0, v50
	v_mul_f32_e32 v1, v1, v50
	v_mul_f32_e32 v6, v6, v51
	v_mul_f32_e32 v7, v7, v51
	v_mul_f32_e32 v4, v4, v51
	v_mul_f32_e32 v5, v5, v51
	v_mul_f32_e32 v14, v14, v52
	v_mul_f32_e32 v15, v15, v52
	v_mul_f32_e32 v12, v12, v52
	v_mul_f32_e32 v13, v13, v52
	v_mul_f32_e32 v10, v10, v53
	v_mul_f32_e32 v11, v11, v53
	v_mul_f32_e32 v8, v8, v53
	v_mul_f32_e32 v9, v9, v53
	v_mul_f32_e32 v22, v22, v54
	v_mul_f32_e32 v23, v23, v54
	v_mul_f32_e32 v20, v20, v54
	v_mul_f32_e32 v21, v21, v54
	v_mul_f32_e32 v18, v18, v55
	v_mul_f32_e32 v19, v19, v55
	v_mul_f32_e32 v16, v16, v55
	v_mul_f32_e32 v17, v17, v55
	v_mul_f32_e32 v30, v30, v56
	v_mul_f32_e32 v31, v31, v56
	v_mul_f32_e32 v28, v28, v56
	v_mul_f32_e32 v29, v29, v56
	v_mul_f32_e32 v26, v26, v57
	v_mul_f32_e32 v27, v27, v57
	v_mul_f32_e32 v24, v24, v57
	v_mul_f32_e32 v25, v25, v57
	s_branch .LBB0_609
